# mlstm_pre: key column sums pre-reduced over the 4 same-column lanes of each DPP row, 16 lanes per wave issue the 32 LDS float atomics (was 16-way same-address conflicts)
# speedup vs baseline: 1.0237x; 1.0237x over previous
; DI void conv32(const bf16_t* __restrict__ Pcol, int tok, int spos, const float* wl, int wstride, float* acc) {
;     ...
; #pragma unroll
;     for (int j = 0; j < 4; ++j) {
;       const bool ok = (spos - 3 + j >= 0);
;       const uint4* src = (const uint4*)(Pcol + (size_t)(tok - 3 + (ok ? j : 3)) * 4096) + 2 * hq;
; #pragma unroll
;       for (int q = 0; q < 2; ++q) {
;         v[j][q] = src[q];
;         if (!ok) v[j][q] = make_uint4(0u, 0u, 0u, 0u);
;       }
;     }
; #pragma unroll
;     for (int i = 0; i < 16; ++i) acc[16 * hq + i] = 0.f;
; #pragma unroll
;     for (int j = 0; j < 4; ++j) {
;       const float4* w4 = (const float4*)(wl + j * wstride + 16 * hq);
; #pragma unroll
;       for (int q = 0; q < 2; ++q) {
;         float f[8];
;         unpack8(v[j][q], f);
;         float4 wa = w4[2 * q], wb = w4[2 * q + 1];
;         float* a = acc + 16 * hq + 8 * q;
;         a[0] += wa.x * f[0]; a[1] += wa.y * f[1]; a[2] += wa.z * f[2]; a[3] += wa.w * f[3];
;         a[4] += wb.x * f[4]; a[5] += wb.y * f[5]; a[6] += wb.z * f[6]; a[7] += wb.w * f[7];
; DI void mlstm_pre(const Params& p, int ch, char* smem) {
;     ...
;   __syncthreads();
;   const int t = tid >> 2, part = tid & 3;
;   const float wgt = __expf(b_last - s_bc[t] + s_li[t] - m_new);
;   {
;     float a[32];
;     conv32(P + 2048 + h * 128 + part * 32, tok0 + t, c * 64 + t, s_w + part * 32, 256, a);
.LBB0_404:
	s_or_b64 exec, exec, s[10:11]
	s_mul_i32 s9, s44, 0xe000
	s_mul_hi_i32 s8, s44, 0xe000
	s_add_u32 s60, s84, s9
	s_waitcnt vmcnt(63) expcnt(7) lgkmcnt(15)
	s_barrier
	ds_read2st64_b32 v[2:3], v2 offset0:136 offset1:138
	s_addc_u32 s61, s85, s8
	s_add_u32 s66, s60, 0x4000
	s_addc_u32 s67, s61, 0
	s_add_u32 s64, s60, 0x8000
	s_addc_u32 s65, s61, 0
	s_waitcnt lgkmcnt(0)
	v_sub_f32_e32 v0, v0, v3
	s_lshl_b32 s34, s34, 8
	v_add_f32_e32 v0, v0, v2
	s_add_u32 s8, s3, s34
	v_sub_f32_e32 v0, v0, v1
	s_addc_u32 s9, s4, 0
	v_add_u32_e32 v8, s70, v79
	v_mul_f32_e32 v0, 0x3fb8aa3b, v0
	v_lshl_add_u64 v[16:17], s[8:9], 0, v[28:29]
	v_add_u32_e32 v9, s90, v79
	v_add_u32_e32 v18, -3, v8
	v_exp_f32_e32 v83, v0
	v_lshlrev_b32_e32 v84, 7, v81
	v_cmp_lt_i32_e64 s[10:11], 2, v9
	v_cmp_lt_i32_e64 s[12:13], 1, v9
	v_cmp_lt_i32_e64 s[14:15], 0, v9
	v_cndmask_b32_e64 v0, v8, v18, s[10:11]
	v_ashrrev_i32_e32 v1, 31, v0
	v_lshlrev_b64 v[10:11], 13, v[0:1]
	v_lshl_add_u64 v[22:23], v[16:17], 0, v[10:11]
	global_load_dwordx4 v[0:3], v[22:23], off offset:16
	global_load_dwordx4 v[4:7], v[22:23], off
	v_cmp_lt_i32_e64 s[8:9], -1, v9
	v_ashrrev_i32_e32 v9, 31, v8
	v_lshlrev_b64 v[8:9], 13, v[8:9]
	v_lshl_add_u64 v[36:37], v[16:17], 0, v[8:9]
	s_waitcnt vmcnt(1)
	v_cndmask_b32_e64 v35, 0, v0, s[10:11]
	v_cndmask_b32_e64 v0, 3, 1, s[12:13]
	v_add_u32_e32 v0, v0, v18
	v_cndmask_b32_e64 v34, 0, v1, s[10:11]
	v_ashrrev_i32_e32 v1, 31, v0
	s_waitcnt vmcnt(0)
	v_cndmask_b32_e64 v24, 0, v7, s[10:11]
	v_cndmask_b32_e64 v25, 0, v6, s[10:11]
	v_lshlrev_b64 v[6:7], 13, v[0:1]
	v_lshl_add_u64 v[20:21], v[16:17], 0, v[6:7]
	v_cndmask_b32_e64 v32, 0, v3, s[10:11]
	v_cndmask_b32_e64 v33, 0, v2, s[10:11]
	global_load_dwordx4 v[0:3], v[20:21], off offset:16
	global_load_dwordx4 v[12:15], v[20:21], off
	v_cndmask_b32_e64 v26, 0, v5, s[10:11]
	v_cndmask_b32_e64 v27, 0, v4, s[10:11]
	v_lshlrev_b32_e32 v58, 16, v26
	v_and_b32_e32 v59, 0xffff0000, v26
	v_lshlrev_b32_e32 v64, 16, v35
	v_and_b32_e32 v65, 0xffff0000, v35
	v_lshlrev_b32_e32 v86, 16, v34
	v_and_b32_e32 v87, 0xffff0000, v34
	v_lshlrev_b32_e32 v88, 16, v33
	v_and_b32_e32 v89, 0xffff0000, v33
	v_lshlrev_b32_e32 v60, 16, v25
	v_and_b32_e32 v61, 0xffff0000, v25
	v_lshlrev_b32_e32 v62, 16, v24
	v_and_b32_e32 v63, 0xffff0000, v24
	s_waitcnt vmcnt(1)
	v_cndmask_b32_e64 v45, 0, v0, s[12:13]
	v_cndmask_b32_e64 v0, 3, 2, s[14:15]
	v_add_u32_e32 v0, v0, v18
	v_cndmask_b32_e64 v44, 0, v1, s[12:13]
	v_ashrrev_i32_e32 v1, 31, v0
	v_lshlrev_b64 v[4:5], 13, v[0:1]
	v_lshl_add_u64 v[18:19], v[16:17], 0, v[4:5]
	s_waitcnt vmcnt(0)
	v_cndmask_b32_e64 v38, 0, v15, s[12:13]
	v_cndmask_b32_e64 v39, 0, v14, s[12:13]
	v_cndmask_b32_e64 v40, 0, v13, s[12:13]
	v_cndmask_b32_e64 v41, 0, v12, s[12:13]
	v_cndmask_b32_e64 v42, 0, v3, s[12:13]
	v_cndmask_b32_e64 v43, 0, v2, s[12:13]
	global_load_dwordx4 v[0:3], v[18:19], off offset:16
	global_load_dwordx4 v[12:15], v[18:19], off
	v_lshlrev_b32_e32 v16, 16, v27
	v_and_b32_e32 v17, 0xffff0000, v27
	v_lshlrev_b32_e32 v26, 16, v41
	v_and_b32_e32 v27, 0xffff0000, v41
	v_lshlrev_b32_e32 v90, 16, v40
	v_and_b32_e32 v91, 0xffff0000, v40
	v_lshlrev_b32_e32 v92, 16, v39
	v_and_b32_e32 v93, 0xffff0000, v39
	v_lshlrev_b32_e32 v94, 16, v38
	v_and_b32_e32 v95, 0xffff0000, v38
	v_lshlrev_b32_e32 v96, 16, v45
	v_and_b32_e32 v97, 0xffff0000, v45
	v_lshlrev_b32_e32 v98, 16, v44
	v_and_b32_e32 v99, 0xffff0000, v44
	v_lshlrev_b32_e32 v100, 16, v43
	v_and_b32_e32 v101, 0xffff0000, v43
	s_waitcnt vmcnt(1)
	v_cndmask_b32_e64 v50, 0, v3, s[14:15]
	s_waitcnt vmcnt(0)
	v_cndmask_b32_e64 v46, 0, v15, s[14:15]
	v_cndmask_b32_e64 v47, 0, v14, s[14:15]
	v_cndmask_b32_e64 v48, 0, v13, s[14:15]
	v_cndmask_b32_e64 v49, 0, v12, s[14:15]
	v_cndmask_b32_e64 v51, 0, v2, s[14:15]
	v_cndmask_b32_e64 v52, 0, v1, s[14:15]
	v_cndmask_b32_e64 v53, 0, v0, s[14:15]
	global_load_dwordx4 v[0:3], v[36:37], off offset:16
	global_load_dwordx4 v[12:15], v[36:37], off
	v_lshlrev_b32_e32 v54, 16, v49
	v_and_b32_e32 v55, 0xffff0000, v49
	v_lshlrev_b32_e32 v102, 16, v48
	v_and_b32_e32 v103, 0xffff0000, v48
	v_lshlrev_b32_e32 v104, 16, v47
	v_and_b32_e32 v105, 0xffff0000, v47
	v_lshlrev_b32_e32 v106, 16, v46
	v_and_b32_e32 v107, 0xffff0000, v46
	v_lshlrev_b32_e32 v108, 16, v53
	v_and_b32_e32 v109, 0xffff0000, v53
	v_lshlrev_b32_e32 v110, 16, v52
	v_and_b32_e32 v111, 0xffff0000, v52
	v_lshlrev_b32_e32 v112, 16, v51
	v_and_b32_e32 v113, 0xffff0000, v51
	v_lshlrev_b32_e32 v24, 16, v50
	v_and_b32_e32 v25, 0xffff0000, v50
	s_waitcnt vmcnt(1)
	v_cndmask_b32_e64 v122, 0, v3, s[8:9]
	s_waitcnt vmcnt(0)
	v_cndmask_b32_e64 v56, 0, v15, s[8:9]
	v_cndmask_b32_e64 v57, 0, v14, s[8:9]
	v_cndmask_b32_e64 v85, 0, v13, s[8:9]
	v_cndmask_b32_e64 v115, 0, v12, s[8:9]
	v_cndmask_b32_e64 v123, 0, v2, s[8:9]
	v_cndmask_b32_e64 v124, 0, v1, s[8:9]
	v_cndmask_b32_e64 v125, 0, v0, s[8:9]
	v_lshlrev_b32_e32 v12, 16, v32
	v_and_b32_e32 v13, 0xffff0000, v32
	v_lshlrev_b32_e32 v14, 16, v42
	v_and_b32_e32 v15, 0xffff0000, v42
	ds_read_b128 v[32:35], v84 offset:40960
	ds_read_b128 v[38:41], v84 offset:40976
	ds_read_b128 v[42:45], v84 offset:40992
	ds_read_b128 v[0:3], v84 offset:41008
	ds_read_b128 v[46:49], v84 offset:41984
	ds_read_b128 v[50:53], v84 offset:43008
	s_waitcnt lgkmcnt(5)
	v_pk_fma_f32 v[16:17], v[32:33], v[16:17], 0 op_sel_hi:[1,1,0]
	v_lshlrev_b32_e32 v118, 16, v57
	v_and_b32_e32 v119, 0xffff0000, v57
	s_waitcnt lgkmcnt(1)
	v_pk_fma_f32 v[16:17], v[46:47], v[26:27], v[16:17]
	v_lshlrev_b32_e32 v120, 16, v56
	v_and_b32_e32 v121, 0xffff0000, v56
	s_waitcnt lgkmcnt(0)
; DI float sigmoidf_(float x) { return __builtin_amdgcn_rcpf(1.f + __expf(-x)); }
; DI void conv32(const bf16_t* __restrict__ Pcol, int tok, int spos, const float* wl, int wstride, float* acc) {
;     ...
; #pragma unroll
;     for (int j = 0; j < 4; ++j) {
;       const bool ok = (spos - 3 + j >= 0);
;       const uint4* src = (const uint4*)(Pcol + (size_t)(tok - 3 + (ok ? j : 3)) * 4096) + 2 * hq;
; #pragma unroll
;       for (int q = 0; q < 2; ++q) {
;         v[j][q] = src[q];
;         if (!ok) v[j][q] = make_uint4(0u, 0u, 0u, 0u);
;       }
;     }
; #pragma unroll
;     for (int i = 0; i < 16; ++i) acc[16 * hq + i] = 0.f;
; #pragma unroll
;     for (int j = 0; j < 4; ++j) {
;       const float4* w4 = (const float4*)(wl + j * wstride + 16 * hq);
; #pragma unroll
;       for (int q = 0; q < 2; ++q) {
;         float f[8];
;         unpack8(v[j][q], f);
;         float4 wa = w4[2 * q], wb = w4[2 * q + 1];
;         float* a = acc + 16 * hq + 8 * q;
;         a[0] += wa.x * f[0]; a[1] += wa.y * f[1]; a[2] += wa.z * f[2]; a[3] += wa.w * f[3];
;         a[4] += wb.x * f[4]; a[5] += wb.y * f[5]; a[6] += wb.z * f[6]; a[7] += wb.w * f[7];
;       }
;     }
; #pragma unroll
;     for (int i = 0; i < 16; ++i) acc[16 * hq + i] = acc[16 * hq + i] * sigmoidf_(acc[16 * hq + i]);
	v_pk_fma_f32 v[16:17], v[50:51], v[54:55], v[16:17]
	ds_read_b128 v[54:57], v84 offset:44032
	v_lshlrev_b32_e32 v114, 16, v115
	v_and_b32_e32 v115, 0xffff0000, v115
	v_pk_fma_f32 v[38:39], v[38:39], v[60:61], 0 op_sel_hi:[1,1,0]
	v_lshlrev_b32_e32 v116, 16, v85
	s_waitcnt lgkmcnt(0)
	v_pk_fma_f32 v[26:27], v[54:55], v[114:115], v[16:17]
	v_pk_fma_f32 v[16:17], v[34:35], v[58:59], 0 op_sel_hi:[1,1,0]
	ds_read_b128 v[32:35], v84 offset:42000
	v_pk_fma_f32 v[16:17], v[48:49], v[90:91], v[16:17]
	ds_read_b128 v[46:49], v84 offset:43024
	v_pk_fma_f32 v[16:17], v[52:53], v[102:103], v[16:17]
	ds_read_b128 v[50:53], v84 offset:44048
	s_waitcnt lgkmcnt(2)
	v_pk_fma_f32 v[32:33], v[32:33], v[92:93], v[38:39]
	v_pk_fma_f32 v[38:39], v[42:43], v[64:65], 0 op_sel_hi:[1,1,0]
	s_waitcnt lgkmcnt(1)
	v_pk_fma_f32 v[32:33], v[46:47], v[104:105], v[32:33]
	v_lshlrev_b32_e32 v54, 16, v125
	s_waitcnt lgkmcnt(0)
	v_pk_fma_f32 v[50:51], v[50:51], v[118:119], v[32:33]
	v_pk_fma_f32 v[32:33], v[40:41], v[62:63], 0 op_sel_hi:[1,1,0]
	v_and_b32_e32 v55, 0xffff0000, v125
	v_pk_fma_f32 v[32:33], v[34:35], v[94:95], v[32:33]
	v_and_b32_e32 v117, 0xffff0000, v85
	v_pk_fma_f32 v[32:33], v[48:49], v[106:107], v[32:33]
	ds_read_b128 v[46:49], v84 offset:44064
	v_pk_fma_f32 v[52:53], v[52:53], v[120:121], v[32:33]
	ds_read_b128 v[32:35], v84 offset:42016
	v_pk_fma_f32 v[16:17], v[56:57], v[116:117], v[16:17]
	v_lshlrev_b32_e32 v56, 16, v124
	v_and_b32_e32 v57, 0xffff0000, v124
	v_pk_fma_f32 v[0:1], v[0:1], v[88:89], 0 op_sel_hi:[1,1,0]
	s_waitcnt lgkmcnt(0)
	v_pk_fma_f32 v[32:33], v[32:33], v[96:97], v[38:39]
	ds_read_b128 v[38:41], v84 offset:43040
	v_lshlrev_b32_e32 v58, 16, v123
	v_and_b32_e32 v59, 0xffff0000, v123
	v_pk_fma_f32 v[2:3], v[2:3], v[12:13], 0 op_sel_hi:[1,1,0]
	v_mul_f32_e32 v12, 0xbfb8aa3b, v26
	s_waitcnt lgkmcnt(0)
	v_pk_fma_f32 v[32:33], v[38:39], v[108:109], v[32:33]
	v_mul_f32_e32 v13, 0xbfb8aa3b, v27
	v_pk_fma_f32 v[54:55], v[46:47], v[54:55], v[32:33]
	v_pk_fma_f32 v[32:33], v[44:45], v[86:87], 0 op_sel_hi:[1,1,0]
	ds_read_b128 v[42:45], v84 offset:43056
	v_pk_fma_f32 v[32:33], v[34:35], v[98:99], v[32:33]
	v_exp_f32_e32 v12, v12
	v_pk_fma_f32 v[32:33], v[40:41], v[110:111], v[32:33]
	ds_read_b128 v[38:41], v84 offset:42032
	v_pk_fma_f32 v[32:33], v[48:49], v[56:57], v[32:33]
	ds_read_b128 v[46:49], v84 offset:44080
	v_mul_f32_e32 v34, 0xbfb8aa3b, v32
	v_mul_f32_e32 v35, 0xbfb8aa3b, v33
	v_exp_f32_e32 v34, v34
	v_exp_f32_e32 v35, v35
	s_waitcnt lgkmcnt(1)
	v_pk_fma_f32 v[0:1], v[38:39], v[100:101], v[0:1]
	v_pk_fma_f32 v[2:3], v[40:41], v[14:15], v[2:3]
	v_add_f32_e32 v34, 1.0, v34
	v_add_f32_e32 v35, 1.0, v35
	v_rcp_f32_e32 v34, v34
	v_rcp_f32_e32 v35, v35
	v_pk_fma_f32 v[0:1], v[42:43], v[112:113], v[0:1]
	v_mul_f32_e32 v14, 0xbfb8aa3b, v16
	s_waitcnt lgkmcnt(0)
	v_pk_fma_f32 v[0:1], v[46:47], v[58:59], v[0:1]
	v_mul_f32_e32 v15, 0xbfb8aa3b, v17
	v_exp_f32_e32 v14, v14
	v_exp_f32_e32 v15, v15
	v_pk_mul_f32 v[32:33], v[32:33], v[34:35]
	v_mul_f32_e32 v34, 0xbfb8aa3b, v0
	v_mul_f32_e32 v35, 0xbfb8aa3b, v1
	v_exp_f32_e32 v13, v13
	v_exp_f32_e32 v34, v34
	v_exp_f32_e32 v35, v35
	v_add_f32_e32 v14, 1.0, v14
	v_add_f32_e32 v15, 1.0, v15
	v_add_f32_e32 v12, 1.0, v12
	v_add_f32_e32 v13, 1.0, v13
	v_rcp_f32_e32 v14, v14
	v_rcp_f32_e32 v15, v15
	v_add_f32_e32 v34, 1.0, v34
	v_add_f32_e32 v35, 1.0, v35
	v_rcp_f32_e32 v12, v12
	v_rcp_f32_e32 v13, v13
	v_rcp_f32_e32 v34, v34
	v_rcp_f32_e32 v35, v35
	v_lshlrev_b32_e32 v60, 16, v122
	v_and_b32_e32 v61, 0xffff0000, v122
	v_pk_fma_f32 v[2:3], v[44:45], v[24:25], v[2:3]
	v_pk_mul_f32 v[14:15], v[16:17], v[14:15]
	v_pk_fma_f32 v[2:3], v[48:49], v[60:61], v[2:3]
	v_mul_f32_e32 v16, 0xbfb8aa3b, v50
	v_mul_f32_e32 v17, 0xbfb8aa3b, v51
	v_mul_f32_e32 v24, 0xbfb8aa3b, v52
	v_mul_f32_e32 v25, 0xbfb8aa3b, v53
	v_pk_mul_f32 v[12:13], v[26:27], v[12:13]
	v_exp_f32_e32 v16, v16
	v_exp_f32_e32 v17, v17
	v_exp_f32_e32 v24, v24
	v_exp_f32_e32 v25, v25
	v_mul_f32_e32 v26, 0xbfb8aa3b, v54
	v_mul_f32_e32 v27, 0xbfb8aa3b, v55
	v_pk_mul_f32 v[34:35], v[0:1], v[34:35]
	v_mul_f32_e32 v0, 0xbfb8aa3b, v2
	v_mul_f32_e32 v1, 0xbfb8aa3b, v3
	v_exp_f32_e32 v26, v26
	v_exp_f32_e32 v27, v27
	v_exp_f32_e32 v0, v0
	v_exp_f32_e32 v1, v1
	v_add_f32_e32 v16, 1.0, v16
	v_add_f32_e32 v17, 1.0, v17
	v_add_f32_e32 v24, 1.0, v24
	v_add_f32_e32 v25, 1.0, v25
	v_rcp_f32_e32 v16, v16
	v_rcp_f32_e32 v17, v17
	v_rcp_f32_e32 v24, v24
	v_rcp_f32_e32 v25, v25
	v_add_f32_e32 v26, 1.0, v26
	v_add_f32_e32 v27, 1.0, v27
	v_add_f32_e32 v0, 1.0, v0
	v_add_f32_e32 v1, 1.0, v1
	v_rcp_f32_e32 v26, v26
	v_rcp_f32_e32 v27, v27
	v_rcp_f32_e32 v0, v0
	v_rcp_f32_e32 v1, v1
	v_pk_mul_f32 v[16:17], v[50:51], v[16:17]
	v_pk_mul_f32 v[24:25], v[52:53], v[24:25]
	v_pk_mul_f32 v[26:27], v[54:55], v[26:27]
	v_pk_mul_f32 v[38:39], v[2:3], v[0:1]
	global_load_dwordx4 v[0:3], v[22:23], off offset:32
	global_load_dwordx4 v[40:43], v[22:23], off offset:48
	global_load_dwordx4 v[44:47], v[20:21], off offset:32
	s_nop 0
	global_load_dwordx4 v[20:23], v[20:21], off offset:48
	s_nop 0
	global_load_dwordx4 v[48:51], v[18:19], off offset:32
	global_load_dwordx4 v[52:55], v[18:19], off offset:48
	global_load_dwordx4 v[56:59], v[36:37], off offset:32
	global_load_dwordx4 v[60:63], v[36:37], off offset:48
	s_waitcnt vmcnt(7)
	v_cndmask_b32_e64 v3, 0, v3, s[10:11]
	v_cndmask_b32_e64 v2, 0, v2, s[10:11]
	v_cndmask_b32_e64 v1, 0, v1, s[10:11]
	v_cndmask_b32_e64 v0, 0, v0, s[10:11]
	s_waitcnt vmcnt(6)
	v_cndmask_b32_e64 v19, 0, v43, s[10:11]
	v_cndmask_b32_e64 v18, 0, v42, s[10:11]
	v_cndmask_b32_e64 v36, 0, v41, s[10:11]
	v_cndmask_b32_e64 v37, 0, v40, s[10:11]
	s_waitcnt vmcnt(5)
; DI float sigmoidf_(float x) { return __builtin_amdgcn_rcpf(1.f + __expf(-x)); }
; DI void conv32(const bf16_t* __restrict__ Pcol, int tok, int spos, const float* wl, int wstride, float* acc) {
;     ...
; #pragma unroll
;     for (int j = 0; j < 4; ++j) {
;       const bool ok = (spos - 3 + j >= 0);
;       const uint4* src = (const uint4*)(Pcol + (size_t)(tok - 3 + (ok ? j : 3)) * 4096) + 2 * hq;
; #pragma unroll
;       for (int q = 0; q < 2; ++q) {
;         v[j][q] = src[q];
;         if (!ok) v[j][q] = make_uint4(0u, 0u, 0u, 0u);
;       }
;     }
; #pragma unroll
;     for (int i = 0; i < 16; ++i) acc[16 * hq + i] = 0.f;
; #pragma unroll
;     for (int j = 0; j < 4; ++j) {
;       const float4* w4 = (const float4*)(wl + j * wstride + 16 * hq);
; #pragma unroll
;       for (int q = 0; q < 2; ++q) {
;         float f[8];
;         unpack8(v[j][q], f);
;         float4 wa = w4[2 * q], wb = w4[2 * q + 1];
;         float* a = acc + 16 * hq + 8 * q;
;         a[0] += wa.x * f[0]; a[1] += wa.y * f[1]; a[2] += wa.z * f[2]; a[3] += wa.w * f[3];
;         a[4] += wb.x * f[4]; a[5] += wb.y * f[5]; a[6] += wb.z * f[6]; a[7] += wb.w * f[7];
;       }
;     }
; #pragma unroll
;     for (int i = 0; i < 16; ++i) acc[16 * hq + i] = acc[16 * hq + i] * sigmoidf_(acc[16 * hq + i]);
	v_cndmask_b32_e64 v40, 0, v47, s[12:13]
	v_cndmask_b32_e64 v41, 0, v46, s[12:13]
	v_cndmask_b32_e64 v42, 0, v45, s[12:13]
	v_cndmask_b32_e64 v43, 0, v44, s[12:13]
	s_waitcnt vmcnt(4)
	v_cndmask_b32_e64 v86, 0, v22, s[12:13]
	s_waitcnt vmcnt(3)
	v_cndmask_b32_e64 v87, 0, v51, s[14:15]
	v_cndmask_b32_e64 v88, 0, v50, s[14:15]
	v_cndmask_b32_e64 v89, 0, v49, s[14:15]
	v_cndmask_b32_e64 v90, 0, v48, s[14:15]
	s_waitcnt vmcnt(2)
	v_cndmask_b32_e64 v91, 0, v55, s[14:15]
	v_cndmask_b32_e64 v92, 0, v54, s[14:15]
	s_waitcnt vmcnt(1)
	v_cndmask_b32_e64 v93, 0, v58, s[8:9]
	v_cndmask_b32_e64 v94, 0, v57, s[8:9]
	v_cndmask_b32_e64 v95, 0, v56, s[8:9]
	v_cndmask_b32_e64 v85, 0, v23, s[12:13]
	v_cndmask_b32_e64 v121, 0, v59, s[8:9]
	s_waitcnt vmcnt(0)
	v_cndmask_b32_e64 v64, 0, v63, s[8:9]
	v_cndmask_b32_e64 v65, 0, v62, s[8:9]
	v_cndmask_b32_e64 v122, 0, v61, s[8:9]
	v_cndmask_b32_e64 v123, 0, v60, s[8:9]
	v_lshlrev_b32_e32 v22, 16, v0
	v_and_b32_e32 v23, 0xffff0000, v0
	v_lshlrev_b32_e32 v102, 16, v1
	v_and_b32_e32 v103, 0xffff0000, v1
	v_lshlrev_b32_e32 v106, 16, v2
	v_and_b32_e32 v107, 0xffff0000, v2
	v_lshlrev_b32_e32 v58, 16, v3
	v_and_b32_e32 v59, 0xffff0000, v3
	v_lshlrev_b32_e32 v50, 16, v37
	v_and_b32_e32 v51, 0xffff0000, v37
	v_lshlrev_b32_e32 v46, 16, v36
	v_and_b32_e32 v47, 0xffff0000, v36
	v_lshlrev_b32_e32 v98, 16, v43
	v_and_b32_e32 v99, 0xffff0000, v43
	v_lshlrev_b32_e32 v104, 16, v42
	v_and_b32_e32 v105, 0xffff0000, v42
	v_lshlrev_b32_e32 v108, 16, v41
	v_and_b32_e32 v109, 0xffff0000, v41
	v_lshlrev_b32_e32 v60, 16, v40
	v_and_b32_e32 v61, 0xffff0000, v40
	v_lshlrev_b32_e32 v40, 16, v86
	v_and_b32_e32 v41, 0xffff0000, v86
	v_lshlrev_b32_e32 v100, 16, v90
	v_and_b32_e32 v101, 0xffff0000, v90
	v_lshlrev_b32_e32 v110, 16, v89
	v_and_b32_e32 v111, 0xffff0000, v89
	v_lshlrev_b32_e32 v112, 16, v88
	v_and_b32_e32 v113, 0xffff0000, v88
	v_lshlrev_b32_e32 v62, 16, v87
	v_and_b32_e32 v63, 0xffff0000, v87
	v_lshlrev_b32_e32 v42, 16, v92
	v_and_b32_e32 v43, 0xffff0000, v92
	v_lshlrev_b32_e32 v36, 16, v91
	v_and_b32_e32 v37, 0xffff0000, v91
	v_lshlrev_b32_e32 v114, 16, v95
	v_and_b32_e32 v115, 0xffff0000, v95
	v_lshlrev_b32_e32 v116, 16, v94
	v_and_b32_e32 v117, 0xffff0000, v94
	v_lshlrev_b32_e32 v118, 16, v93
	v_and_b32_e32 v119, 0xffff0000, v93
	ds_read_b128 v[0:3], v84 offset:41024
	ds_read_b128 v[86:89], v84 offset:42048
	ds_read_b128 v[90:93], v84 offset:43072
	ds_read_b128 v[94:97], v84 offset:44096
	v_cndmask_b32_e64 v21, 0, v21, s[12:13]
	s_waitcnt lgkmcnt(3)
	v_pk_fma_f32 v[0:1], v[0:1], v[22:23], 0 op_sel_hi:[1,1,0]
	v_cndmask_b32_e64 v20, 0, v20, s[12:13]
	s_waitcnt lgkmcnt(2)
	v_pk_fma_f32 v[0:1], v[86:87], v[98:99], v[0:1]
	v_cndmask_b32_e64 v55, 0, v53, s[14:15]
	s_waitcnt lgkmcnt(1)
	v_pk_fma_f32 v[0:1], v[90:91], v[100:101], v[0:1]
	ds_read_b128 v[98:101], v84 offset:41040
	s_waitcnt lgkmcnt(1)
	v_pk_fma_f32 v[22:23], v[94:95], v[114:115], v[0:1]
	v_cndmask_b32_e64 v54, 0, v52, s[14:15]
	v_mul_f32_e32 v0, 0xbfb8aa3b, v22
	v_exp_f32_e32 v0, v0
	v_mul_f32_e32 v1, 0xbfb8aa3b, v23
	v_exp_f32_e32 v1, v1
	v_lshlrev_b32_e32 v52, 16, v20
	v_add_f32_e32 v0, 1.0, v0
	v_rcp_f32_e32 v90, v0
	v_add_f32_e32 v0, 1.0, v1
	v_rcp_f32_e32 v91, v0
	v_pk_fma_f32 v[0:1], v[2:3], v[102:103], 0 op_sel_hi:[1,1,0]
	v_and_b32_e32 v53, 0xffff0000, v20
	v_pk_fma_f32 v[0:1], v[88:89], v[104:105], v[0:1]
	v_lshlrev_b32_e32 v48, 16, v21
	v_pk_fma_f32 v[0:1], v[92:93], v[110:111], v[0:1]
	v_and_b32_e32 v49, 0xffff0000, v21
	v_pk_fma_f32 v[110:111], v[96:97], v[116:117], v[0:1]
	v_lshlrev_b32_e32 v20, 16, v85
	v_mul_f32_e32 v0, 0xbfb8aa3b, v110
	v_and_b32_e32 v21, 0xffff0000, v85
	v_exp_f32_e32 v85, v0
	ds_read_b128 v[86:89], v84 offset:41056
	ds_read_b128 v[0:3], v84 offset:41072
	v_pk_mul_f32 v[22:23], v[22:23], v[90:91]
	ds_read_b128 v[90:93], v84 offset:42064
	ds_read_b128 v[94:97], v84 offset:43088
	ds_read_b128 v[102:105], v84 offset:44112
	s_waitcnt lgkmcnt(5)
	v_pk_fma_f32 v[98:99], v[98:99], v[106:107], 0 op_sel_hi:[1,1,0]
	v_pk_fma_f32 v[58:59], v[100:101], v[58:59], 0 op_sel_hi:[1,1,0]
	s_waitcnt lgkmcnt(2)
	v_pk_fma_f32 v[90:91], v[90:91], v[108:109], v[98:99]
	v_add_f32_e32 v85, 1.0, v85
	s_waitcnt lgkmcnt(1)
	v_pk_fma_f32 v[90:91], v[94:95], v[112:113], v[90:91]
	v_pk_fma_f32 v[58:59], v[92:93], v[60:61], v[58:59]
	v_lshlrev_b32_e32 v120, 16, v121
	v_and_b32_e32 v121, 0xffff0000, v121
	v_rcp_f32_e32 v114, v85
	v_mul_f32_e32 v85, 0xbfb8aa3b, v111
	s_waitcnt lgkmcnt(0)
	v_pk_fma_f32 v[98:99], v[102:103], v[118:119], v[90:91]
	v_pk_fma_f32 v[58:59], v[96:97], v[62:63], v[58:59]
	v_exp_f32_e32 v85, v85
	v_mul_f32_e32 v90, 0xbfb8aa3b, v98
	v_pk_fma_f32 v[62:63], v[104:105], v[120:121], v[58:59]
	v_exp_f32_e32 v90, v90
	v_mul_f32_e32 v91, 0xbfb8aa3b, v99
	v_mul_f32_e32 v58, 0xbfb8aa3b, v62
	v_exp_f32_e32 v91, v91
	v_exp_f32_e32 v58, v58
	v_mul_f32_e32 v59, 0xbfb8aa3b, v63
	v_exp_f32_e32 v59, v59
	v_add_f32_e32 v85, 1.0, v85
	v_rcp_f32_e32 v115, v85
	v_add_f32_e32 v85, 1.0, v90
	v_rcp_f32_e32 v102, v85
	v_add_f32_e32 v85, 1.0, v91
	v_add_f32_e32 v58, 1.0, v58
	v_rcp_f32_e32 v103, v85
	v_rcp_f32_e32 v100, v58
	v_add_f32_e32 v85, 1.0, v59
	ds_read_b128 v[58:61], v84 offset:42080
	ds_read_b128 v[90:93], v84 offset:43104
	ds_read_b128 v[94:97], v84 offset:44128
	v_rcp_f32_e32 v101, v85
	v_pk_fma_f32 v[50:51], v[86:87], v[50:51], 0 op_sel_hi:[1,1,0]
	v_lshlrev_b32_e32 v56, 16, v54
	v_and_b32_e32 v57, 0xffff0000, v54
	s_waitcnt lgkmcnt(2)
	v_pk_fma_f32 v[50:51], v[58:59], v[52:53], v[50:51]
	v_pk_fma_f32 v[46:47], v[88:89], v[46:47], 0 op_sel_hi:[1,1,0]
	v_lshlrev_b32_e32 v54, 16, v55
	v_and_b32_e32 v55, 0xffff0000, v55
	s_waitcnt lgkmcnt(1)
; DI int fragoff(int row, int k, int KS) { return (((row >> 4) * KS + (k >> 5)) << 9) + (((((k >> 3) & 3) << 4) + (row & 15)) << 3) + (k & 7); }
; DI void mlstm_pre(const Params& p, int ch, char* smem) {
;     ...
;     conv32(P + 2048 + h * 128 + part * 32, tok0 + t, c * 64 + t, s_w + part * 32, 256, a);
; #pragma unroll
;     for (int q = 0; q < 4; ++q) *(uint4*)(qs + t * 136 + part * 32 + 8 * q) = pack8(a + 8 * q);
;     {
;       const float sct = s_sc[t];
; #pragma unroll
;       for (int i = 0; i < 32; ++i) a[i] *= sct;
; #pragma unroll
;       for (int q = 0; q < 4; ++q) *(uint4*)(o_q + fragoff(t, part * 32 + 8 * q, 4)) = pack8(a + 8 * q);
;     }
;     conv32(P + 2560 + h * 128 + part * 32, tok0 + t, c * 64 + t, s_w + 128 + part * 32, 256, a);
	v_pk_fma_f32 v[50:51], v[90:91], v[56:57], v[50:51]
	v_lshlrev_b32_e32 v52, 16, v123
	v_and_b32_e32 v53, 0xffff0000, v123
	v_pk_fma_f32 v[46:47], v[60:61], v[48:49], v[46:47]
	s_waitcnt lgkmcnt(0)
	v_pk_fma_f32 v[58:59], v[94:95], v[52:53], v[50:51]
	v_pk_fma_f32 v[46:47], v[92:93], v[54:55], v[46:47]
	v_lshlrev_b32_e32 v48, 16, v122
	v_and_b32_e32 v49, 0xffff0000, v122
	v_pk_mul_f32 v[56:57], v[62:63], v[100:101]
	v_mul_f32_e32 v63, 0xbfb8aa3b, v59
	v_pk_fma_f32 v[54:55], v[96:97], v[48:49], v[46:47]
	v_mul_f32_e32 v50, 0xbfb8aa3b, v58
	v_exp_f32_e32 v63, v63
	v_mul_f32_e32 v46, 0xbfb8aa3b, v54
	v_exp_f32_e32 v85, v50
	v_exp_f32_e32 v46, v46
	v_add_f32_e32 v47, 1.0, v63
	v_rcp_f32_e32 v91, v47
	v_add_f32_e32 v62, 1.0, v85
	v_add_f32_e32 v46, 1.0, v46
	v_mul_f32_e32 v47, 0xbfb8aa3b, v55
	v_rcp_f32_e32 v90, v62
	v_exp_f32_e32 v85, v47
	v_rcp_f32_e32 v92, v46
	ds_read_b128 v[46:49], v84 offset:42096
	ds_read_b128 v[60:63], v84 offset:43120
	ds_read_b128 v[86:89], v84 offset:44144
	v_lshlrev_b32_e32 v44, 16, v18
	v_and_b32_e32 v45, 0xffff0000, v18
	v_lshlrev_b32_e32 v18, 16, v19
	v_and_b32_e32 v19, 0xffff0000, v19
	v_pk_fma_f32 v[2:3], v[2:3], v[18:19], 0 op_sel_hi:[1,1,0]
	v_pk_fma_f32 v[0:1], v[0:1], v[44:45], 0 op_sel_hi:[1,1,0]
	s_waitcnt lgkmcnt(2)
	v_pk_fma_f32 v[2:3], v[48:49], v[20:21], v[2:3]
	v_pk_fma_f32 v[0:1], v[46:47], v[40:41], v[0:1]
	s_waitcnt lgkmcnt(1)
	v_pk_fma_f32 v[2:3], v[62:63], v[36:37], v[2:3]
	v_lshlrev_b32_e32 v18, 16, v64
	v_and_b32_e32 v19, 0xffff0000, v64
	v_pk_fma_f32 v[0:1], v[60:61], v[42:43], v[0:1]
	v_lshlrev_b32_e32 v40, 16, v65
	v_and_b32_e32 v41, 0xffff0000, v65
	s_waitcnt lgkmcnt(0)
	v_pk_fma_f32 v[2:3], v[88:89], v[18:19], v[2:3]
	v_pk_fma_f32 v[0:1], v[86:87], v[40:41], v[0:1]
	v_mul_f32_e32 v18, 0xbfb8aa3b, v2
	v_mul_f32_e32 v19, 0xbfb8aa3b, v3
	v_mul_f32_e32 v40, 0xbfb8aa3b, v0
	v_mul_f32_e32 v41, 0xbfb8aa3b, v1
	v_exp_f32_e32 v18, v18
	v_exp_f32_e32 v19, v19
	v_exp_f32_e32 v40, v40
	v_exp_f32_e32 v41, v41
	v_add_f32_e32 v18, 1.0, v18
	v_add_f32_e32 v19, 1.0, v19
	v_add_f32_e32 v85, 1.0, v85
	v_add_f32_e32 v40, 1.0, v40
	v_add_f32_e32 v41, 1.0, v41
	v_rcp_f32_e32 v18, v18
	v_rcp_f32_e32 v19, v19
	v_rcp_f32_e32 v93, v85
	v_rcp_f32_e32 v40, v40
	v_rcp_f32_e32 v41, v41
	v_pk_mul_f32 v[20:21], v[58:59], v[90:91]
	v_pk_mul_f32 v[18:19], v[2:3], v[18:19]
	v_pk_mul_f32 v[50:51], v[110:111], v[114:115]
	v_pk_mul_f32 v[52:53], v[98:99], v[102:103]
	v_pk_mul_f32 v[36:37], v[54:55], v[92:93]
	v_pk_mul_f32 v[40:41], v[0:1], v[40:41]
	v_mul_lo_u32 v42, v79, s75
	v_add_u32_e32 v85, v42, v28
	v_cvt_pk_bf16_f32 v0, v12, v13
	v_cvt_pk_bf16_f32 v1, v14, v15
	v_cvt_pk_bf16_f32 v2, v16, v17
	v_cvt_pk_bf16_f32 v3, v24, v25
	ds_write_b128 v85, v[0:3]
	v_cvt_pk_bf16_f32 v0, v26, v27
	v_cvt_pk_bf16_f32 v1, v32, v33
	v_cvt_pk_bf16_f32 v2, v34, v35
	v_cvt_pk_bf16_f32 v3, v38, v39
	ds_write_b128 v85, v[0:3] offset:16
	v_cvt_pk_bf16_f32 v0, v22, v23
	v_cvt_pk_bf16_f32 v1, v50, v51
	v_cvt_pk_bf16_f32 v2, v52, v53
	v_cvt_pk_bf16_f32 v3, v56, v57
	ds_write_b128 v85, v[0:3] offset:32
	v_cvt_pk_bf16_f32 v0, v20, v21
	v_cvt_pk_bf16_f32 v1, v36, v37
	v_cvt_pk_bf16_f32 v2, v40, v41
	v_cvt_pk_bf16_f32 v3, v18, v19
	s_movk_i32 s45, 0xfef4
	ds_write_b128 v85, v[0:3] offset:48
	v_mad_u64_u32 v[0:1], s[70:71], v79, s45, v[42:43]
	ds_read_b32 v0, v0 offset:37408
	s_add_u32 s70, s5, s34
	s_addc_u32 s71, s20, 0
	s_waitcnt lgkmcnt(0)
	v_pk_mul_f32 v[2:3], v[12:13], v[0:1] op_sel_hi:[1,0]
	v_pk_mul_f32 v[12:13], v[14:15], v[0:1] op_sel_hi:[1,0]
	v_pk_mul_f32 v[14:15], v[16:17], v[0:1] op_sel_hi:[1,0]
	v_pk_mul_f32 v[16:17], v[24:25], v[0:1] op_sel_hi:[1,0]
	v_pk_mul_f32 v[24:25], v[26:27], v[0:1] op_sel_hi:[1,0]
	v_pk_mul_f32 v[26:27], v[32:33], v[0:1] op_sel_hi:[1,0]
	v_pk_mul_f32 v[32:33], v[34:35], v[0:1] op_sel_hi:[1,0]
	v_pk_mul_f32 v[34:35], v[38:39], v[0:1] op_sel_hi:[1,0]
	v_pk_mul_f32 v[22:23], v[22:23], v[0:1] op_sel_hi:[1,0]
	v_pk_mul_f32 v[38:39], v[50:51], v[0:1] op_sel_hi:[1,0]
	v_pk_mul_f32 v[42:43], v[52:53], v[0:1] op_sel_hi:[1,0]
	v_pk_mul_f32 v[44:45], v[56:57], v[0:1] op_sel_hi:[1,0]
	v_pk_mul_f32 v[20:21], v[20:21], v[0:1] op_sel_hi:[1,0]
	v_pk_mul_f32 v[36:37], v[36:37], v[0:1] op_sel_hi:[1,0]
	v_pk_mul_f32 v[40:41], v[40:41], v[0:1] op_sel_hi:[1,0]
	v_pk_mul_f32 v[18:19], v[18:19], v[0:1] op_sel_hi:[1,0]
	v_lshrrev_b32_e32 v0, 2, v79
	v_lshlrev_b32_e32 v1, 3, v79
	v_and_or_b32 v0, v0, s76, v81
	v_and_b32_e32 v1, 0x78, v1
	v_lshl_or_b32 v46, v0, 9, v1
	v_ashrrev_i32_e32 v47, 31, v46
	v_cvt_pk_bf16_f32 v0, v2, v3
	v_cvt_pk_bf16_f32 v1, v12, v13
	v_cvt_pk_bf16_f32 v2, v14, v15
	v_cvt_pk_bf16_f32 v3, v16, v17
	v_lshl_add_u64 v[12:13], v[46:47], 1, s[60:61]
	global_store_dwordx4 v[12:13], v[0:3], off
	v_lshl_add_u64 v[16:17], s[70:71], 0, v[28:29]
	s_nop 0
	v_cvt_pk_bf16_f32 v0, v24, v25
	v_cvt_pk_bf16_f32 v1, v26, v27
	v_cvt_pk_bf16_f32 v2, v32, v33
	v_cvt_pk_bf16_f32 v3, v34, v35
	global_store_dwordx4 v[12:13], v[0:3], off offset:256
	s_nop 1
	v_cvt_pk_bf16_f32 v0, v22, v23
	v_cvt_pk_bf16_f32 v1, v38, v39
	v_cvt_pk_bf16_f32 v2, v42, v43
	v_cvt_pk_bf16_f32 v3, v44, v45
	global_store_dwordx4 v[12:13], v[0:3], off offset:512
	s_nop 1
	v_cvt_pk_bf16_f32 v0, v20, v21
	v_cvt_pk_bf16_f32 v1, v36, v37
	v_cvt_pk_bf16_f32 v2, v40, v41
	v_cvt_pk_bf16_f32 v3, v18, v19
	global_store_dwordx4 v[12:13], v[0:3], off offset:768
	v_lshl_add_u64 v[10:11], v[16:17], 0, v[10:11]
	global_load_dwordx4 v[0:3], v[10:11], off offset:16
	global_load_dwordx4 v[12:15], v[10:11], off
	v_lshl_add_u64 v[6:7], v[16:17], 0, v[6:7]
	v_lshl_add_u64 v[4:5], v[16:17], 0, v[4:5]
	s_waitcnt vmcnt(1)
	v_cndmask_b32_e64 v24, 0, v3, s[10:11]
	s_waitcnt vmcnt(0)
; DI float sigmoidf_(float x) { return __builtin_amdgcn_rcpf(1.f + __expf(-x)); }
; DI void conv32(const bf16_t* __restrict__ Pcol, int tok, int spos, const float* wl, int wstride, float* acc) {
;     ...
; #pragma unroll
;     for (int j = 0; j < 4; ++j) {
;       const bool ok = (spos - 3 + j >= 0);
;       const uint4* src = (const uint4*)(Pcol + (size_t)(tok - 3 + (ok ? j : 3)) * 4096) + 2 * hq;
; #pragma unroll
;       for (int q = 0; q < 2; ++q) {
;         v[j][q] = src[q];
;         if (!ok) v[j][q] = make_uint4(0u, 0u, 0u, 0u);
;       }
;     }
; #pragma unroll
;     for (int i = 0; i < 16; ++i) acc[16 * hq + i] = 0.f;
; #pragma unroll
;     for (int j = 0; j < 4; ++j) {
;       const float4* w4 = (const float4*)(wl + j * wstride + 16 * hq);
; #pragma unroll
;       for (int q = 0; q < 2; ++q) {
;         float f[8];
;         unpack8(v[j][q], f);
;         float4 wa = w4[2 * q], wb = w4[2 * q + 1];
;         float* a = acc + 16 * hq + 8 * q;
;         a[0] += wa.x * f[0]; a[1] += wa.y * f[1]; a[2] += wa.z * f[2]; a[3] += wa.w * f[3];
;         a[4] += wb.x * f[4]; a[5] += wb.y * f[5]; a[6] += wb.z * f[6]; a[7] += wb.w * f[7];
;       }
;     }
; #pragma unroll
;     for (int i = 0; i < 16; ++i) acc[16 * hq + i] = acc[16 * hq + i] * sigmoidf_(acc[16 * hq + i]);
	v_cndmask_b32_e64 v20, 0, v15, s[10:11]
	v_cndmask_b32_e64 v21, 0, v14, s[10:11]
	v_cndmask_b32_e64 v23, 0, v13, s[10:11]
	v_cndmask_b32_e64 v19, 0, v12, s[10:11]
	v_cndmask_b32_e64 v25, 0, v2, s[10:11]
	v_cndmask_b32_e64 v26, 0, v1, s[10:11]
	v_cndmask_b32_e64 v27, 0, v0, s[10:11]
	global_load_dwordx4 v[0:3], v[6:7], off offset:16
	global_load_dwordx4 v[12:15], v[6:7], off
	v_lshlrev_b32_e32 v56, 16, v27
	v_and_b32_e32 v57, 0xffff0000, v27
	v_lshlrev_b32_e32 v58, 16, v26
	v_and_b32_e32 v59, 0xffff0000, v26
	v_lshlrev_b32_e32 v60, 16, v25
	v_and_b32_e32 v61, 0xffff0000, v25
	v_lshlrev_b32_e32 v18, 16, v19
	v_and_b32_e32 v19, 0xffff0000, v19
	v_lshlrev_b32_e32 v52, 16, v21
	v_and_b32_e32 v53, 0xffff0000, v21
	v_lshlrev_b32_e32 v54, 16, v20
	v_and_b32_e32 v55, 0xffff0000, v20
	v_lshlrev_b32_e32 v22, 16, v23
	v_and_b32_e32 v23, 0xffff0000, v23
	s_waitcnt vmcnt(1)
	v_cndmask_b32_e64 v36, 0, v3, s[12:13]
	s_waitcnt vmcnt(0)
	v_cndmask_b32_e64 v32, 0, v15, s[12:13]
	v_cndmask_b32_e64 v33, 0, v14, s[12:13]
	v_cndmask_b32_e64 v34, 0, v13, s[12:13]
	v_cndmask_b32_e64 v35, 0, v12, s[12:13]
	v_cndmask_b32_e64 v37, 0, v2, s[12:13]
	v_cndmask_b32_e64 v38, 0, v1, s[12:13]
	v_cndmask_b32_e64 v39, 0, v0, s[12:13]
	global_load_dwordx4 v[0:3], v[4:5], off offset:16
	global_load_dwordx4 v[12:15], v[4:5], off
	v_lshlrev_b32_e32 v44, 16, v35
	v_and_b32_e32 v45, 0xffff0000, v35
	v_lshlrev_b32_e32 v62, 16, v34
	v_and_b32_e32 v63, 0xffff0000, v34
	v_lshlrev_b32_e32 v64, 16, v33
	v_and_b32_e32 v65, 0xffff0000, v33
	v_lshlrev_b32_e32 v86, 16, v32
	v_and_b32_e32 v87, 0xffff0000, v32
	v_lshlrev_b32_e32 v88, 16, v39
	v_and_b32_e32 v89, 0xffff0000, v39
	v_lshlrev_b32_e32 v90, 16, v38
	v_and_b32_e32 v91, 0xffff0000, v38
	v_lshlrev_b32_e32 v92, 16, v37
	v_and_b32_e32 v93, 0xffff0000, v37
	s_waitcnt vmcnt(1)
	v_cndmask_b32_e64 v46, 0, v3, s[14:15]
	s_waitcnt vmcnt(0)
	v_cndmask_b32_e64 v42, 0, v13, s[14:15]
	v_cndmask_b32_e64 v43, 0, v12, s[14:15]
	v_lshl_add_u64 v[12:13], v[16:17], 0, v[8:9]
	v_cndmask_b32_e64 v40, 0, v15, s[14:15]
	v_cndmask_b32_e64 v41, 0, v14, s[14:15]
	v_cndmask_b32_e64 v47, 0, v2, s[14:15]
	v_cndmask_b32_e64 v50, 0, v1, s[14:15]
	v_cndmask_b32_e64 v51, 0, v0, s[14:15]
	global_load_dwordx4 v[0:3], v[12:13], off offset:16
	global_load_dwordx4 v[14:17], v[12:13], off
	v_lshlrev_b32_e32 v48, 16, v43
	v_and_b32_e32 v49, 0xffff0000, v43
	v_lshlrev_b32_e32 v94, 16, v42
	v_and_b32_e32 v95, 0xffff0000, v42
	v_lshlrev_b32_e32 v96, 16, v41
	v_and_b32_e32 v97, 0xffff0000, v41
	v_lshlrev_b32_e32 v98, 16, v40
	v_and_b32_e32 v99, 0xffff0000, v40
	v_lshlrev_b32_e32 v104, 16, v47
	v_and_b32_e32 v105, 0xffff0000, v47
	v_lshlrev_b32_e32 v20, 16, v46
	v_and_b32_e32 v21, 0xffff0000, v46
	v_lshlrev_b32_e32 v100, 16, v51
	v_and_b32_e32 v101, 0xffff0000, v51
	v_lshlrev_b32_e32 v102, 16, v50
	v_and_b32_e32 v103, 0xffff0000, v50
	s_waitcnt vmcnt(1)
	v_cndmask_b32_e64 v114, 0, v3, s[8:9]
	s_waitcnt vmcnt(0)
	v_cndmask_b32_e64 v113, 0, v17, s[8:9]
	v_cndmask_b32_e64 v111, 0, v16, s[8:9]
	v_cndmask_b32_e64 v109, 0, v15, s[8:9]
	v_cndmask_b32_e64 v107, 0, v14, s[8:9]
	v_cndmask_b32_e64 v115, 0, v2, s[8:9]
	v_cndmask_b32_e64 v116, 0, v1, s[8:9]
	v_cndmask_b32_e64 v117, 0, v0, s[8:9]
	v_lshlrev_b32_e32 v14, 16, v24
	v_and_b32_e32 v15, 0xffff0000, v24
	v_lshlrev_b32_e32 v16, 16, v36
	v_and_b32_e32 v17, 0xffff0000, v36
	ds_read_b128 v[24:27], v84 offset:41472
	ds_read_b128 v[32:35], v84 offset:41488
	ds_read_b128 v[36:39], v84 offset:41504
	ds_read_b128 v[0:3], v84 offset:41520
	ds_read_b128 v[40:43], v84 offset:42496
	s_waitcnt lgkmcnt(4)
	v_pk_fma_f32 v[18:19], v[24:25], v[18:19], 0 op_sel_hi:[1,1,0]
	v_lshlrev_b32_e32 v106, 16, v107
	v_and_b32_e32 v107, 0xffff0000, v107
	v_lshlrev_b32_e32 v108, 16, v109
	s_waitcnt lgkmcnt(0)
	v_pk_fma_f32 v[18:19], v[40:41], v[44:45], v[18:19]
	ds_read_b128 v[44:47], v84 offset:43520
	v_and_b32_e32 v109, 0xffff0000, v109
	v_lshlrev_b32_e32 v110, 16, v111
	v_and_b32_e32 v111, 0xffff0000, v111
	v_pk_fma_f32 v[36:37], v[36:37], v[56:57], 0 op_sel_hi:[1,1,0]
	s_waitcnt lgkmcnt(0)
	v_pk_fma_f32 v[18:19], v[44:45], v[48:49], v[18:19]
	ds_read_b128 v[48:51], v84 offset:44544
	v_lshlrev_b32_e32 v112, 16, v113
	v_and_b32_e32 v113, 0xffff0000, v113
	v_pk_fma_f32 v[0:1], v[0:1], v[60:61], 0 op_sel_hi:[1,1,0]
	s_waitcnt lgkmcnt(0)
	v_pk_fma_f32 v[24:25], v[48:49], v[106:107], v[18:19]
	v_pk_fma_f32 v[18:19], v[26:27], v[22:23], 0 op_sel_hi:[1,1,0]
	v_pk_fma_f32 v[22:23], v[32:33], v[52:53], 0 op_sel_hi:[1,1,0]
	v_pk_fma_f32 v[18:19], v[42:43], v[62:63], v[18:19]
	ds_read_b128 v[40:43], v84 offset:42512
	v_pk_fma_f32 v[18:19], v[46:47], v[94:95], v[18:19]
	ds_read_b128 v[44:47], v84 offset:43536
	v_pk_fma_f32 v[18:19], v[50:51], v[108:109], v[18:19]
	ds_read_b128 v[48:51], v84 offset:44560
	s_waitcnt lgkmcnt(2)
	v_pk_fma_f32 v[22:23], v[40:41], v[64:65], v[22:23]
	v_lshlrev_b32_e32 v52, 16, v115
	s_waitcnt lgkmcnt(1)
	v_pk_fma_f32 v[22:23], v[44:45], v[96:97], v[22:23]
	v_and_b32_e32 v53, 0xffff0000, v115
	s_waitcnt lgkmcnt(0)
	v_pk_fma_f32 v[26:27], v[48:49], v[110:111], v[22:23]
	v_pk_fma_f32 v[22:23], v[34:35], v[54:55], 0 op_sel_hi:[1,1,0]
	ds_read_b128 v[32:35], v84 offset:42528
	v_pk_fma_f32 v[22:23], v[42:43], v[86:87], v[22:23]
	ds_read_b128 v[40:43], v84 offset:43552
	v_pk_fma_f32 v[22:23], v[46:47], v[98:99], v[22:23]
	ds_read_b128 v[44:47], v84 offset:44576
	s_waitcnt lgkmcnt(2)
	v_pk_fma_f32 v[32:33], v[32:33], v[88:89], v[36:37]
	v_pk_fma_f32 v[48:49], v[50:51], v[112:113], v[22:23]
	v_lshlrev_b32_e32 v22, 16, v117
	v_and_b32_e32 v23, 0xffff0000, v117
	s_waitcnt lgkmcnt(1)
	v_pk_fma_f32 v[32:33], v[40:41], v[100:101], v[32:33]
	v_lshlrev_b32_e32 v54, 16, v114
	s_waitcnt lgkmcnt(0)
; DI float sigmoidf_(float x) { return __builtin_amdgcn_rcpf(1.f + __expf(-x)); }
; DI void conv32(const bf16_t* __restrict__ Pcol, int tok, int spos, const float* wl, int wstride, float* acc) {
;     ...
; #pragma unroll
;     for (int j = 0; j < 4; ++j) {
;       const bool ok = (spos - 3 + j >= 0);
;       const uint4* src = (const uint4*)(Pcol + (size_t)(tok - 3 + (ok ? j : 3)) * 4096) + 2 * hq;
; #pragma unroll
;       for (int q = 0; q < 2; ++q) {
;         v[j][q] = src[q];
;         if (!ok) v[j][q] = make_uint4(0u, 0u, 0u, 0u);
;       }
;     }
; #pragma unroll
;     for (int i = 0; i < 16; ++i) acc[16 * hq + i] = 0.f;
; #pragma unroll
;     for (int j = 0; j < 4; ++j) {
;       const float4* w4 = (const float4*)(wl + j * wstride + 16 * hq);
; #pragma unroll
;       for (int q = 0; q < 2; ++q) {
;         float f[8];
;         unpack8(v[j][q], f);
;         float4 wa = w4[2 * q], wb = w4[2 * q + 1];
;         float* a = acc + 16 * hq + 8 * q;
;         a[0] += wa.x * f[0]; a[1] += wa.y * f[1]; a[2] += wa.z * f[2]; a[3] += wa.w * f[3];
;         a[4] += wb.x * f[4]; a[5] += wb.y * f[5]; a[6] += wb.z * f[6]; a[7] += wb.w * f[7];
;       }
;     }
; #pragma unroll
;     for (int i = 0; i < 16; ++i) acc[16 * hq + i] = acc[16 * hq + i] * sigmoidf_(acc[16 * hq + i]);
	v_pk_fma_f32 v[44:45], v[44:45], v[22:23], v[32:33]
	v_pk_fma_f32 v[22:23], v[38:39], v[58:59], 0 op_sel_hi:[1,1,0]
	ds_read_b128 v[36:39], v84 offset:43568
	v_pk_fma_f32 v[22:23], v[34:35], v[90:91], v[22:23]
	ds_read_b128 v[32:35], v84 offset:42544
	v_pk_fma_f32 v[22:23], v[42:43], v[102:103], v[22:23]
	ds_read_b128 v[40:43], v84 offset:44592
	v_and_b32_e32 v55, 0xffff0000, v114
	v_lshlrev_b32_e32 v50, 16, v116
	s_waitcnt lgkmcnt(1)
	v_pk_fma_f32 v[0:1], v[32:33], v[92:93], v[0:1]
	v_and_b32_e32 v51, 0xffff0000, v116
	v_pk_fma_f32 v[0:1], v[36:37], v[104:105], v[0:1]
	v_pk_fma_f32 v[22:23], v[46:47], v[50:51], v[22:23]
	s_waitcnt lgkmcnt(0)
	v_pk_fma_f32 v[32:33], v[40:41], v[52:53], v[0:1]
	v_pk_fma_f32 v[0:1], v[2:3], v[14:15], 0 op_sel_hi:[1,1,0]
	v_mul_f32_e32 v2, 0xbfb8aa3b, v18
	v_pk_fma_f32 v[0:1], v[34:35], v[16:17], v[0:1]
	v_mul_f32_e32 v3, 0xbfb8aa3b, v19
	v_pk_fma_f32 v[0:1], v[38:39], v[20:21], v[0:1]
	v_exp_f32_e32 v2, v2
	v_pk_fma_f32 v[20:21], v[42:43], v[54:55], v[0:1]
	v_mul_f32_e32 v0, 0xbfb8aa3b, v24
	v_mul_f32_e32 v1, 0xbfb8aa3b, v25
	v_exp_f32_e32 v0, v0
	v_exp_f32_e32 v1, v1
	v_exp_f32_e32 v3, v3
	v_add_f32_e32 v2, 1.0, v2
	v_add_f32_e32 v0, 1.0, v0
	v_add_f32_e32 v1, 1.0, v1
	v_rcp_f32_e32 v0, v0
	v_rcp_f32_e32 v1, v1
	v_add_f32_e32 v3, 1.0, v3
	v_rcp_f32_e32 v2, v2
	v_rcp_f32_e32 v3, v3
	v_pk_mul_f32 v[0:1], v[24:25], v[0:1]
	v_mul_f32_e32 v24, 0xbfb8aa3b, v22
	v_mul_f32_e32 v25, 0xbfb8aa3b, v23
	v_exp_f32_e32 v24, v24
	v_exp_f32_e32 v25, v25
	v_pk_mul_f32 v[2:3], v[18:19], v[2:3]
	v_mul_f32_e32 v14, 0xbfb8aa3b, v26
	v_add_f32_e32 v24, 1.0, v24
	v_add_f32_e32 v25, 1.0, v25
	v_rcp_f32_e32 v24, v24
	v_rcp_f32_e32 v25, v25
	v_mul_f32_e32 v15, 0xbfb8aa3b, v27
	v_mul_f32_e32 v16, 0xbfb8aa3b, v48
	v_mul_f32_e32 v17, 0xbfb8aa3b, v49
	v_pk_mul_f32 v[64:65], v[22:23], v[24:25]
	v_mul_f32_e32 v22, 0xbfb8aa3b, v32
	v_mul_f32_e32 v23, 0xbfb8aa3b, v33
	v_exp_f32_e32 v22, v22
	v_exp_f32_e32 v23, v23
	v_mul_f32_e32 v18, 0xbfb8aa3b, v44
	v_mul_f32_e32 v19, 0xbfb8aa3b, v45
	v_add_f32_e32 v22, 1.0, v22
	v_add_f32_e32 v23, 1.0, v23
	v_rcp_f32_e32 v22, v22
	v_rcp_f32_e32 v23, v23
	v_exp_f32_e32 v14, v14
	v_exp_f32_e32 v15, v15
	v_exp_f32_e32 v16, v16
	v_exp_f32_e32 v17, v17
	v_exp_f32_e32 v18, v18
	v_exp_f32_e32 v19, v19
	v_pk_mul_f32 v[88:89], v[32:33], v[22:23]
	v_mul_f32_e32 v22, 0xbfb8aa3b, v20
	v_mul_f32_e32 v23, 0xbfb8aa3b, v21
	v_exp_f32_e32 v22, v22
	v_exp_f32_e32 v23, v23
	v_add_f32_e32 v14, 1.0, v14
	v_add_f32_e32 v15, 1.0, v15
	v_add_f32_e32 v16, 1.0, v16
	v_add_f32_e32 v17, 1.0, v17
	v_add_f32_e32 v18, 1.0, v18
	v_add_f32_e32 v19, 1.0, v19
	v_rcp_f32_e32 v14, v14
	v_rcp_f32_e32 v15, v15
	v_rcp_f32_e32 v16, v16
	v_rcp_f32_e32 v17, v17
	v_rcp_f32_e32 v18, v18
	v_rcp_f32_e32 v19, v19
	v_add_f32_e32 v22, 1.0, v22
	v_add_f32_e32 v23, 1.0, v23
	v_rcp_f32_e32 v22, v22
	v_rcp_f32_e32 v23, v23
	v_pk_mul_f32 v[14:15], v[26:27], v[14:15]
	v_pk_mul_f32 v[16:17], v[48:49], v[16:17]
	v_pk_mul_f32 v[18:19], v[44:45], v[18:19]
	v_pk_mul_f32 v[90:91], v[20:21], v[22:23]
	global_load_dwordx4 v[20:23], v[10:11], off offset:32
	global_load_dwordx4 v[24:27], v[10:11], off offset:48
	global_load_dwordx4 v[32:35], v[6:7], off offset:32
	global_load_dwordx4 v[36:39], v[6:7], off offset:48
	global_load_dwordx4 v[40:43], v[4:5], off offset:32
	s_nop 0
	global_load_dwordx4 v[4:7], v[4:5], off offset:48
	s_nop 0
	global_load_dwordx4 v[44:47], v[12:13], off offset:32
	s_nop 0
	global_load_dwordx4 v[10:13], v[12:13], off offset:48
	v_pk_mul_f32 v[18:19], v[18:19], s[36:37] op_sel_hi:[1,0]
	s_waitcnt vmcnt(7)
	v_cndmask_b32_e64 v20, 0, v20, s[10:11]
	s_waitcnt vmcnt(6)
	v_cndmask_b32_e64 v27, 0, v27, s[10:11]
	v_cndmask_b32_e64 v26, 0, v26, s[10:11]
	v_cndmask_b32_e64 v25, 0, v25, s[10:11]
	v_cndmask_b32_e64 v24, 0, v24, s[10:11]
	s_waitcnt vmcnt(5)
	v_cndmask_b32_e64 v52, 0, v35, s[12:13]
	v_cndmask_b32_e64 v53, 0, v34, s[12:13]
	v_cndmask_b32_e64 v54, 0, v33, s[12:13]
	v_cndmask_b32_e64 v55, 0, v32, s[12:13]
	s_waitcnt vmcnt(4)
	v_cndmask_b32_e64 v56, 0, v39, s[12:13]
	v_cndmask_b32_e64 v57, 0, v38, s[12:13]
	v_cndmask_b32_e64 v37, 0, v37, s[12:13]
	v_cndmask_b32_e64 v36, 0, v36, s[12:13]
	s_waitcnt vmcnt(3)
	v_cndmask_b32_e64 v41, 0, v41, s[14:15]
	v_cndmask_b32_e64 v40, 0, v40, s[14:15]
	s_waitcnt vmcnt(2)
	v_cndmask_b32_e64 v62, 0, v7, s[14:15]
	v_cndmask_b32_e64 v63, 0, v6, s[14:15]
	v_cndmask_b32_e64 v92, 0, v5, s[14:15]
	v_cndmask_b32_e64 v93, 0, v4, s[14:15]
	s_waitcnt vmcnt(1)
	v_cndmask_b32_e64 v94, 0, v47, s[8:9]
	v_cndmask_b32_e64 v95, 0, v46, s[8:9]
	v_cndmask_b32_e64 v96, 0, v45, s[8:9]
	v_cndmask_b32_e64 v97, 0, v44, s[8:9]
	v_cndmask_b32_e64 v61, 0, v43, s[14:15]
	v_cndmask_b32_e64 v60, 0, v42, s[14:15]
	s_waitcnt vmcnt(0)
; DI float sigmoidf_(float x) { return __builtin_amdgcn_rcpf(1.f + __expf(-x)); }
; DI void conv32(const bf16_t* __restrict__ Pcol, int tok, int spos, const float* wl, int wstride, float* acc) {
;     ...
; #pragma unroll
;     for (int j = 0; j < 4; ++j) {
;       const bool ok = (spos - 3 + j >= 0);
;       const uint4* src = (const uint4*)(Pcol + (size_t)(tok - 3 + (ok ? j : 3)) * 4096) + 2 * hq;
; #pragma unroll
;       for (int q = 0; q < 2; ++q) {
;         v[j][q] = src[q];
;         if (!ok) v[j][q] = make_uint4(0u, 0u, 0u, 0u);
;       }
;     }
; #pragma unroll
;     for (int i = 0; i < 16; ++i) acc[16 * hq + i] = 0.f;
; #pragma unroll
;     for (int j = 0; j < 4; ++j) {
;       const float4* w4 = (const float4*)(wl + j * wstride + 16 * hq);
; #pragma unroll
;       for (int q = 0; q < 2; ++q) {
;         float f[8];
;         unpack8(v[j][q], f);
;         float4 wa = w4[2 * q], wb = w4[2 * q + 1];
;         float* a = acc + 16 * hq + 8 * q;
;         a[0] += wa.x * f[0]; a[1] += wa.y * f[1]; a[2] += wa.z * f[2]; a[3] += wa.w * f[3];
;         a[4] += wb.x * f[4]; a[5] += wb.y * f[5]; a[6] += wb.z * f[6]; a[7] += wb.w * f[7];
;       }
;     }
; #pragma unroll
;     for (int i = 0; i < 16; ++i) acc[16 * hq + i] = acc[16 * hq + i] * sigmoidf_(acc[16 * hq + i]);
	v_cndmask_b32_e64 v86, 0, v13, s[8:9]
	v_cndmask_b32_e64 v87, 0, v12, s[8:9]
	v_cndmask_b32_e64 v124, 0, v11, s[8:9]
	v_cndmask_b32_e64 v125, 0, v10, s[8:9]
	v_lshlrev_b32_e32 v4, 16, v20
	v_and_b32_e32 v5, 0xffff0000, v20
	v_lshlrev_b32_e32 v38, 16, v24
	v_and_b32_e32 v39, 0xffff0000, v24
	v_lshlrev_b32_e32 v50, 16, v25
	v_and_b32_e32 v51, 0xffff0000, v25
	v_lshlrev_b32_e32 v48, 16, v26
	v_and_b32_e32 v49, 0xffff0000, v26
	v_lshlrev_b32_e32 v32, 16, v27
	v_and_b32_e32 v33, 0xffff0000, v27
	v_lshlrev_b32_e32 v6, 16, v55
	v_and_b32_e32 v7, 0xffff0000, v55
	v_lshlrev_b32_e32 v108, 16, v54
	v_and_b32_e32 v109, 0xffff0000, v54
	v_lshlrev_b32_e32 v110, 16, v53
	v_and_b32_e32 v111, 0xffff0000, v53
	v_lshlrev_b32_e32 v58, 16, v52
	v_and_b32_e32 v59, 0xffff0000, v52
	v_lshlrev_b32_e32 v42, 16, v36
	v_and_b32_e32 v43, 0xffff0000, v36
	v_lshlrev_b32_e32 v52, 16, v37
	v_and_b32_e32 v53, 0xffff0000, v37
	v_lshlrev_b32_e32 v44, 16, v57
	v_and_b32_e32 v45, 0xffff0000, v57
	v_lshlrev_b32_e32 v36, 16, v56
	v_and_b32_e32 v37, 0xffff0000, v56
	v_lshlrev_b32_e32 v112, 16, v40
	v_and_b32_e32 v113, 0xffff0000, v40
	v_lshlrev_b32_e32 v114, 16, v41
	v_and_b32_e32 v115, 0xffff0000, v41
	v_lshlrev_b32_e32 v56, 16, v93
	v_and_b32_e32 v57, 0xffff0000, v93
	v_lshlrev_b32_e32 v54, 16, v92
	v_and_b32_e32 v55, 0xffff0000, v92
	v_lshlrev_b32_e32 v46, 16, v63
	v_and_b32_e32 v47, 0xffff0000, v63
	v_lshlrev_b32_e32 v40, 16, v62
	v_and_b32_e32 v41, 0xffff0000, v62
	v_lshlrev_b32_e32 v118, 16, v97
	v_and_b32_e32 v119, 0xffff0000, v97
	v_lshlrev_b32_e32 v120, 16, v96
	v_and_b32_e32 v121, 0xffff0000, v96
	v_lshlrev_b32_e32 v122, 16, v95
	v_and_b32_e32 v123, 0xffff0000, v95
	v_lshlrev_b32_e32 v62, 16, v94
	v_and_b32_e32 v63, 0xffff0000, v94
	v_pk_mul_f32 v[26:27], v[0:1], s[36:37] op_sel_hi:[1,0]
	v_pk_mul_f32 v[24:25], v[2:3], s[36:37] op_sel_hi:[1,0]
	v_pk_mul_f32 v[12:13], v[88:89], s[36:37] op_sel_hi:[1,0]
	v_pk_mul_f32 v[10:11], v[90:91], s[36:37] op_sel_hi:[1,0]
	ds_read_b128 v[0:3], v84 offset:41536
	ds_read_b128 v[88:91], v84 offset:42560
	ds_read_b128 v[92:95], v84 offset:43584
	ds_read_b128 v[96:99], v84 offset:44608
	ds_read_b128 v[100:103], v84 offset:41552
	s_waitcnt lgkmcnt(4)
	v_pk_fma_f32 v[0:1], v[0:1], v[4:5], 0 op_sel_hi:[1,1,0]
	v_cndmask_b32_e64 v23, 0, v23, s[10:11]
	s_waitcnt lgkmcnt(3)
	v_pk_fma_f32 v[0:1], v[88:89], v[6:7], v[0:1]
	v_cndmask_b32_e64 v22, 0, v22, s[10:11]
	s_waitcnt lgkmcnt(2)
	v_pk_fma_f32 v[0:1], v[92:93], v[112:113], v[0:1]
	v_lshlrev_b32_e32 v106, 16, v22
	v_and_b32_e32 v107, 0xffff0000, v22
	v_lshlrev_b32_e32 v34, 16, v23
	v_and_b32_e32 v35, 0xffff0000, v23
	v_pk_mul_f32 v[22:23], v[14:15], s[36:37] op_sel_hi:[1,0]
	s_waitcnt lgkmcnt(1)
	v_pk_fma_f32 v[14:15], v[96:97], v[118:119], v[0:1]
	v_cndmask_b32_e64 v21, 0, v21, s[10:11]
	v_mul_f32_e32 v0, 0xbfb8aa3b, v14
	v_exp_f32_e32 v0, v0
	v_mul_f32_e32 v1, 0xbfb8aa3b, v15
	v_exp_f32_e32 v1, v1
	v_lshlrev_b32_e32 v104, 16, v21
	v_add_f32_e32 v0, 1.0, v0
	v_and_b32_e32 v105, 0xffff0000, v21
	v_pk_mul_f32 v[20:21], v[16:17], s[36:37] op_sel_hi:[1,0]
	v_pk_mul_f32 v[16:17], v[64:65], s[36:37] op_sel_hi:[1,0]
	v_rcp_f32_e32 v64, v0
	v_add_f32_e32 v0, 1.0, v1
	v_rcp_f32_e32 v65, v0
	v_pk_fma_f32 v[0:1], v[2:3], v[104:105], 0 op_sel_hi:[1,1,0]
	ds_read_b128 v[4:7], v84 offset:41568
	v_pk_fma_f32 v[0:1], v[90:91], v[108:109], v[0:1]
	v_pk_mul_f32 v[14:15], v[14:15], v[64:65]
	v_pk_fma_f32 v[0:1], v[94:95], v[114:115], v[0:1]
	s_waitcnt lgkmcnt(1)
	v_pk_fma_f32 v[100:101], v[100:101], v[106:107], 0 op_sel_hi:[1,1,0]
	v_pk_fma_f32 v[104:105], v[98:99], v[120:121], v[0:1]
	v_lshlrev_b32_e32 v116, 16, v60
	v_mul_f32_e32 v0, 0xbfb8aa3b, v104
	v_exp_f32_e32 v88, v0
	ds_read_b128 v[0:3], v84 offset:41584
	v_and_b32_e32 v117, 0xffff0000, v60
	v_mul_f32_e32 v65, 0xbfb8aa3b, v105
	v_add_f32_e32 v64, 1.0, v88
	ds_read_b128 v[88:91], v84 offset:42576
	ds_read_b128 v[92:95], v84 offset:43600
	ds_read_b128 v[96:99], v84 offset:44624
	v_pk_fma_f32 v[34:35], v[102:103], v[34:35], 0 op_sel_hi:[1,1,0]
	v_lshlrev_b32_e32 v60, 16, v61
	s_waitcnt lgkmcnt(2)
	v_pk_fma_f32 v[88:89], v[88:89], v[110:111], v[100:101]
	v_and_b32_e32 v61, 0xffff0000, v61
	s_waitcnt lgkmcnt(1)
	v_pk_fma_f32 v[88:89], v[92:93], v[116:117], v[88:89]
	v_exp_f32_e32 v65, v65
	s_waitcnt lgkmcnt(0)
	v_pk_fma_f32 v[88:89], v[96:97], v[122:123], v[88:89]
	v_pk_fma_f32 v[34:35], v[90:91], v[58:59], v[34:35]
	v_mul_f32_e32 v92, 0xbfb8aa3b, v88
	v_mul_f32_e32 v93, 0xbfb8aa3b, v89
	v_exp_f32_e32 v92, v92
	v_exp_f32_e32 v93, v93
	v_pk_fma_f32 v[34:35], v[94:95], v[60:61], v[34:35]
	v_add_f32_e32 v65, 1.0, v65
	v_add_f32_e32 v92, 1.0, v92
	v_add_f32_e32 v93, 1.0, v93
	v_rcp_f32_e32 v92, v92
	v_rcp_f32_e32 v93, v93
	v_pk_fma_f32 v[94:95], v[98:99], v[62:63], v[34:35]
	v_rcp_f32_e32 v64, v64
	v_mul_f32_e32 v34, 0xbfb8aa3b, v94
	v_exp_f32_e32 v58, v34
	v_rcp_f32_e32 v65, v65
	v_mul_f32_e32 v59, 0xbfb8aa3b, v95
	v_pk_mul_f32 v[92:93], v[88:89], v[92:93]
	v_exp_f32_e32 v88, v59
	v_add_f32_e32 v58, 1.0, v58
	v_pk_mul_f32 v[34:35], v[104:105], v[64:65]
	v_rcp_f32_e32 v96, v58
	ds_read_b128 v[58:61], v84 offset:42592
	ds_read_b128 v[62:65], v84 offset:43616
	v_add_f32_e32 v97, 1.0, v88
	ds_read_b128 v[88:91], v84 offset:44640
	v_pk_fma_f32 v[4:5], v[4:5], v[38:39], 0 op_sel_hi:[1,1,0]
	v_lshlrev_b32_e32 v38, 16, v125
	s_waitcnt lgkmcnt(2)
	v_pk_fma_f32 v[4:5], v[58:59], v[42:43], v[4:5]
	v_and_b32_e32 v39, 0xffff0000, v125
	s_waitcnt lgkmcnt(1)
	v_pk_fma_f32 v[4:5], v[62:63], v[56:57], v[4:5]
	v_pk_fma_f32 v[6:7], v[6:7], v[50:51], 0 op_sel_hi:[1,1,0]
	s_waitcnt lgkmcnt(0)
; DI bf16_t f2bf(float f) { return (bf16_t)(pk2(f, 0.f) & 0xffffu); }
; DI float bf2f(bf16_t h) { return __uint_as_float(((unsigned)h) << 16); }
; DI int fragoff(int row, int k, int KS) { return (((row >> 4) * KS + (k >> 5)) << 9) + (((((k >> 3) & 3) << 4) + (row & 15)) << 3) + (k & 7); }
; DI void mlstm_pre(const Params& p, int ch, char* smem) {
;     ...
;     for (int i = 0; i < 32; ++i) a[i] *= 0.08838834764831845f;
; #pragma unroll
;     for (int q = 0; q < 4; ++q) *(uint4*)(ks + t * 136 + part * 32 + 8 * q) = pack8(a + 8 * q);
; #pragma unroll
;     for (int i = 0; i < 32; ++i) {
;       bf16_t kb = f2bf(a[i] * wgt);
;       o_kwT[fragoff(part * 32 + i, t, 2)] = kb;
;       atomicAdd(&s_kw[part * 32 + i], bf2f(kb));
	v_pk_fma_f32 v[4:5], v[88:89], v[38:39], v[4:5]
	v_pk_fma_f32 v[6:7], v[60:61], v[52:53], v[6:7]
	v_mul_f32_e32 v38, 0xbfb8aa3b, v4
	v_exp_f32_e32 v38, v38
	v_mul_f32_e32 v39, 0xbfb8aa3b, v5
	v_exp_f32_e32 v39, v39
	v_pk_fma_f32 v[6:7], v[64:65], v[54:55], v[6:7]
	v_lshlrev_b32_e32 v50, 16, v124
	v_and_b32_e32 v51, 0xffff0000, v124
	v_pk_fma_f32 v[6:7], v[90:91], v[50:51], v[6:7]
	v_add_f32_e32 v38, 1.0, v38
	v_mul_f32_e32 v50, 0xbfb8aa3b, v6
	v_rcp_f32_e32 v56, v38
	v_add_f32_e32 v38, 1.0, v39
	v_exp_f32_e32 v50, v50
	v_mul_f32_e32 v51, 0xbfb8aa3b, v7
	v_rcp_f32_e32 v57, v38
	v_exp_f32_e32 v51, v51
	v_add_f32_e32 v50, 1.0, v50
	v_rcp_f32_e32 v62, v50
	v_pk_mul_f32 v[4:5], v[4:5], v[56:57]
	v_add_f32_e32 v58, 1.0, v51
	ds_read_b128 v[50:53], v84 offset:42608
	ds_read_b128 v[54:57], v84 offset:43632
	v_rcp_f32_e32 v63, v58
	ds_read_b128 v[58:61], v84 offset:44656
	v_pk_fma_f32 v[0:1], v[0:1], v[48:49], 0 op_sel_hi:[1,1,0]
	v_pk_fma_f32 v[2:3], v[2:3], v[32:33], 0 op_sel_hi:[1,1,0]
	s_waitcnt lgkmcnt(2)
	v_pk_fma_f32 v[0:1], v[50:51], v[44:45], v[0:1]
	v_pk_fma_f32 v[2:3], v[52:53], v[36:37], v[2:3]
	s_waitcnt lgkmcnt(1)
	v_pk_fma_f32 v[0:1], v[54:55], v[46:47], v[0:1]
	v_lshlrev_b32_e32 v44, 16, v87
	v_and_b32_e32 v45, 0xffff0000, v87
	v_pk_fma_f32 v[2:3], v[56:57], v[40:41], v[2:3]
	v_lshlrev_b32_e32 v32, 16, v86
	v_and_b32_e32 v33, 0xffff0000, v86
	s_waitcnt lgkmcnt(0)
	v_pk_fma_f32 v[0:1], v[58:59], v[44:45], v[0:1]
	v_pk_fma_f32 v[36:37], v[60:61], v[32:33], v[2:3]
	v_mul_f32_e32 v44, 0xbfb8aa3b, v0
	v_mul_f32_e32 v45, 0xbfb8aa3b, v1
	v_mul_f32_e32 v2, 0xbfb8aa3b, v36
	v_exp_f32_e32 v44, v44
	v_exp_f32_e32 v45, v45
	v_exp_f32_e32 v2, v2
	v_mul_f32_e32 v3, 0xbfb8aa3b, v37
	v_exp_f32_e32 v3, v3
	v_add_f32_e32 v44, 1.0, v44
	v_add_f32_e32 v45, 1.0, v45
	v_add_f32_e32 v2, 1.0, v2
	v_rcp_f32_e32 v44, v44
	v_rcp_f32_e32 v45, v45
	v_rcp_f32_e32 v40, v2
	v_add_f32_e32 v2, 1.0, v3
	v_rcp_f32_e32 v97, v97
	v_rcp_f32_e32 v41, v2
	v_pk_mul_f32 v[0:1], v[0:1], v[44:45]
	v_pk_mul_f32 v[14:15], v[14:15], s[36:37] op_sel_hi:[1,0]
	v_pk_mul_f32 v[38:39], v[94:95], v[96:97]
	v_pk_mul_f32 v[4:5], v[4:5], s[36:37] op_sel_hi:[1,0]
	v_pk_mul_f32 v[6:7], v[6:7], v[62:63]
	v_pk_mul_f32 v[2:3], v[0:1], s[36:37] op_sel_hi:[1,0]
	v_pk_mul_f32 v[0:1], v[36:37], v[40:41]
	v_pk_mul_f32 v[34:35], v[34:35], s[36:37] op_sel_hi:[1,0]
	v_pk_mul_f32 v[42:43], v[92:93], s[36:37] op_sel_hi:[1,0]
	v_pk_mul_f32 v[38:39], v[38:39], s[36:37] op_sel_hi:[1,0]
	v_pk_mul_f32 v[32:33], v[6:7], s[36:37] op_sel_hi:[1,0]
	v_cvt_pk_bf16_f32 v44, v26, v27
	v_cvt_pk_bf16_f32 v45, v24, v25
	v_cvt_pk_bf16_f32 v46, v22, v23
	v_cvt_pk_bf16_f32 v47, v20, v21
	ds_write_b128 v85, v[44:47] offset:17408
	v_cvt_pk_bf16_f32 v44, v18, v19
	v_cvt_pk_bf16_f32 v45, v16, v17
	v_cvt_pk_bf16_f32 v46, v12, v13
	v_cvt_pk_bf16_f32 v47, v10, v11
	v_lshlrev_b32_e32 v6, 4, v79
	v_pk_mul_f32 v[0:1], v[0:1], s[36:37] op_sel_hi:[1,0]
	ds_write_b128 v85, v[44:47] offset:17424
	v_cvt_pk_bf16_f32 v44, v14, v15
	v_cvt_pk_bf16_f32 v45, v34, v35
	v_cvt_pk_bf16_f32 v46, v42, v43
	v_cvt_pk_bf16_f32 v47, v38, v39
	v_and_b32_e32 v57, 0x180, v6
	v_mul_f32_e32 v6, v83, v26
	ds_write_b128 v85, v[44:47] offset:17440
	v_cvt_pk_bf16_f32 v44, v4, v5
	v_cvt_pk_bf16_f32 v45, v32, v33
	v_cvt_pk_bf16_f32 v46, v2, v3
	v_cvt_pk_bf16_f32 v47, v0, v1
	v_lshrrev_b32_e32 v56, 5, v79
	v_cvt_pk_bf16_f32 v26, v6, s0
	v_lshlrev_b32_e32 v6, 11, v81
	ds_write_b128 v85, v[44:47] offset:17456
	v_bfe_u32 v85, v30, 2, 3
	v_lshl_add_u32 v6, v56, 9, v6
	v_or_b32_e32 v58, v6, v85
	v_or_b32_e32 v6, v58, v57
	v_ashrrev_i32_e32 v7, 31, v6
	v_lshlrev_b64 v[6:7], 1, v[6:7]
	v_lshl_add_u64 v[36:37], s[66:67], 0, v[6:7]
	global_store_short v[36:37], v26, off
	v_lshlrev_b32_e32 v26, 16, v26
	s_nop 1
	v_add_f32_dpp v200, v26, v26 row_ror:8 row_mask:0xf bank_mask:0xf
	s_nop 1
	v_add_f32_dpp v200, v200, v200 row_ror:4 row_mask:0xf bank_mask:0xf
	v_mul_f32_e32 v26, v83, v27
	v_or_b32_e32 v59, 8, v57
	v_cvt_pk_bf16_f32 v40, v26, s0
	v_or_b32_e32 v26, v58, v59
	v_ashrrev_i32_e32 v27, 31, v26
	v_lshlrev_b64 v[26:27], 1, v[26:27]
	v_lshl_add_u64 v[36:37], s[66:67], 0, v[26:27]
	global_store_short v[36:37], v40, off
	v_lshlrev_b32_e32 v36, 16, v40
	v_or_b32_e32 v60, 16, v57
	s_nop 1
	v_add_f32_dpp v201, v36, v36 row_ror:8 row_mask:0xf bank_mask:0xf
	s_nop 1
	v_add_f32_dpp v201, v201, v201 row_ror:4 row_mask:0xf bank_mask:0xf
	v_or_b32_e32 v36, v58, v60
	v_ashrrev_i32_e32 v37, 31, v36
	v_mul_f32_e32 v24, v83, v24
	v_lshlrev_b64 v[36:37], 1, v[36:37]
	v_cvt_pk_bf16_f32 v24, v24, s0
	v_lshl_add_u64 v[40:41], s[66:67], 0, v[36:37]
	global_store_short v[40:41], v24, off
	v_lshlrev_b32_e32 v24, 16, v24
	s_nop 1
	v_add_f32_dpp v202, v24, v24 row_ror:8 row_mask:0xf bank_mask:0xf
	s_nop 1
	v_add_f32_dpp v202, v202, v202 row_ror:4 row_mask:0xf bank_mask:0xf
	v_mul_f32_e32 v24, v83, v25
	v_or_b32_e32 v61, 24, v57
	v_cvt_pk_bf16_f32 v44, v24, s0
	v_or_b32_e32 v24, v58, v61
	v_ashrrev_i32_e32 v25, 31, v24
	v_lshlrev_b64 v[24:25], 1, v[24:25]
	v_lshl_add_u64 v[40:41], s[66:67], 0, v[24:25]
	global_store_short v[40:41], v44, off
	v_lshlrev_b32_e32 v40, 16, v44
	v_or_b32_e32 v62, 32, v57
	s_nop 1
	v_add_f32_dpp v203, v40, v40 row_ror:8 row_mask:0xf bank_mask:0xf
	s_nop 1
	v_add_f32_dpp v203, v203, v203 row_ror:4 row_mask:0xf bank_mask:0xf
	v_or_b32_e32 v40, v58, v62
	v_ashrrev_i32_e32 v41, 31, v40
	v_mul_f32_e32 v22, v83, v22
	v_lshlrev_b64 v[40:41], 1, v[40:41]
	v_cvt_pk_bf16_f32 v22, v22, s0
	v_lshl_add_u64 v[44:45], s[66:67], 0, v[40:41]
	global_store_short v[44:45], v22, off
	v_lshlrev_b32_e32 v22, 16, v22
	s_nop 1
	v_add_f32_dpp v204, v22, v22 row_ror:8 row_mask:0xf bank_mask:0xf
; DI bf16_t f2bf(float f) { return (bf16_t)(pk2(f, 0.f) & 0xffffu); }
; DI float bf2f(bf16_t h) { return __uint_as_float(((unsigned)h) << 16); }
; DI int fragoff(int row, int k, int KS) { return (((row >> 4) * KS + (k >> 5)) << 9) + (((((k >> 3) & 3) << 4) + (row & 15)) << 3) + (k & 7); }
; DI void mlstm_pre(const Params& p, int ch, char* smem) {
;     ...
;     for (int i = 0; i < 32; ++i) {
;       bf16_t kb = f2bf(a[i] * wgt);
;       o_kwT[fragoff(part * 32 + i, t, 2)] = kb;
;       atomicAdd(&s_kw[part * 32 + i], bf2f(kb));
	s_nop 1
	v_add_f32_dpp v204, v204, v204 row_ror:4 row_mask:0xf bank_mask:0xf
	v_mul_f32_e32 v22, v83, v23
	v_or_b32_e32 v63, 40, v57
	v_cvt_pk_bf16_f32 v46, v22, s0
	v_or_b32_e32 v22, v58, v63
	v_ashrrev_i32_e32 v23, 31, v22
	v_lshlrev_b64 v[22:23], 1, v[22:23]
	v_lshl_add_u64 v[44:45], s[66:67], 0, v[22:23]
	global_store_short v[44:45], v46, off
	v_lshlrev_b32_e32 v44, 16, v46
	v_or_b32_e32 v64, 48, v57
	s_nop 1
	v_add_f32_dpp v205, v44, v44 row_ror:8 row_mask:0xf bank_mask:0xf
	s_nop 1
	v_add_f32_dpp v205, v205, v205 row_ror:4 row_mask:0xf bank_mask:0xf
	v_or_b32_e32 v44, v58, v64
	v_ashrrev_i32_e32 v45, 31, v44
	v_mul_f32_e32 v20, v83, v20
	v_lshlrev_b64 v[44:45], 1, v[44:45]
	v_cvt_pk_bf16_f32 v20, v20, s0
	v_lshl_add_u64 v[46:47], s[66:67], 0, v[44:45]
	global_store_short v[46:47], v20, off
	v_lshlrev_b32_e32 v20, 16, v20
	s_nop 1
	v_add_f32_dpp v206, v20, v20 row_ror:8 row_mask:0xf bank_mask:0xf
	s_nop 1
	v_add_f32_dpp v206, v206, v206 row_ror:4 row_mask:0xf bank_mask:0xf
	v_mul_f32_e32 v20, v83, v21
	v_or_b32_e32 v65, 56, v57
	v_cvt_pk_bf16_f32 v48, v20, s0
	v_or_b32_e32 v20, v58, v65
	v_ashrrev_i32_e32 v21, 31, v20
	v_lshlrev_b64 v[20:21], 1, v[20:21]
	v_lshl_add_u64 v[46:47], s[66:67], 0, v[20:21]
	global_store_short v[46:47], v48, off
	v_lshlrev_b32_e32 v46, 16, v48
	v_or_b32_e32 v86, 64, v57
	s_nop 1
	v_add_f32_dpp v207, v46, v46 row_ror:8 row_mask:0xf bank_mask:0xf
	s_nop 1
	v_add_f32_dpp v207, v207, v207 row_ror:4 row_mask:0xf bank_mask:0xf
	v_or_b32_e32 v46, v58, v86
	v_ashrrev_i32_e32 v47, 31, v46
	v_mul_f32_e32 v18, v83, v18
	v_lshlrev_b64 v[46:47], 1, v[46:47]
	v_cvt_pk_bf16_f32 v18, v18, s0
	v_lshl_add_u64 v[48:49], s[66:67], 0, v[46:47]
	global_store_short v[48:49], v18, off
	v_lshlrev_b32_e32 v18, 16, v18
	s_nop 1
	v_add_f32_dpp v208, v18, v18 row_ror:8 row_mask:0xf bank_mask:0xf
	s_nop 1
	v_add_f32_dpp v208, v208, v208 row_ror:4 row_mask:0xf bank_mask:0xf
	v_mul_f32_e32 v18, v83, v19
	v_or_b32_e32 v87, 0x48, v57
	v_cvt_pk_bf16_f32 v50, v18, s0
	v_or_b32_e32 v18, v58, v87
	v_ashrrev_i32_e32 v19, 31, v18
	v_lshlrev_b64 v[18:19], 1, v[18:19]
	v_lshl_add_u64 v[48:49], s[66:67], 0, v[18:19]
	global_store_short v[48:49], v50, off
	v_lshlrev_b32_e32 v48, 16, v50
	v_or_b32_e32 v88, 0x50, v57
	s_nop 1
	v_add_f32_dpp v209, v48, v48 row_ror:8 row_mask:0xf bank_mask:0xf
	s_nop 1
	v_add_f32_dpp v209, v209, v209 row_ror:4 row_mask:0xf bank_mask:0xf
	v_or_b32_e32 v48, v58, v88
	v_ashrrev_i32_e32 v49, 31, v48
	v_mul_f32_e32 v16, v83, v16
	v_lshlrev_b64 v[48:49], 1, v[48:49]
	v_cvt_pk_bf16_f32 v16, v16, s0
	v_lshl_add_u64 v[50:51], s[66:67], 0, v[48:49]
	global_store_short v[50:51], v16, off
	v_lshlrev_b32_e32 v16, 16, v16
	s_nop 1
	v_add_f32_dpp v210, v16, v16 row_ror:8 row_mask:0xf bank_mask:0xf
	s_nop 1
	v_add_f32_dpp v210, v210, v210 row_ror:4 row_mask:0xf bank_mask:0xf
	v_mul_f32_e32 v16, v83, v17
	v_or_b32_e32 v89, 0x58, v57
	v_cvt_pk_bf16_f32 v52, v16, s0
	v_or_b32_e32 v16, v58, v89
	v_ashrrev_i32_e32 v17, 31, v16
	v_lshlrev_b64 v[16:17], 1, v[16:17]
	v_lshl_add_u64 v[50:51], s[66:67], 0, v[16:17]
	global_store_short v[50:51], v52, off
	v_lshlrev_b32_e32 v50, 16, v52
	v_or_b32_e32 v90, 0x60, v57
	s_nop 1
	v_add_f32_dpp v211, v50, v50 row_ror:8 row_mask:0xf bank_mask:0xf
	s_nop 1
	v_add_f32_dpp v211, v211, v211 row_ror:4 row_mask:0xf bank_mask:0xf
	v_or_b32_e32 v50, v58, v90
	v_ashrrev_i32_e32 v51, 31, v50
	v_mul_f32_e32 v12, v83, v12
	v_lshlrev_b64 v[50:51], 1, v[50:51]
	v_cvt_pk_bf16_f32 v12, v12, s0
	v_lshl_add_u64 v[52:53], s[66:67], 0, v[50:51]
	global_store_short v[52:53], v12, off
	v_lshlrev_b32_e32 v12, 16, v12
	s_nop 1
	v_add_f32_dpp v212, v12, v12 row_ror:8 row_mask:0xf bank_mask:0xf
	s_nop 1
	v_add_f32_dpp v212, v212, v212 row_ror:4 row_mask:0xf bank_mask:0xf
	v_mul_f32_e32 v12, v83, v13
	v_or_b32_e32 v91, 0x68, v57
	v_cvt_pk_bf16_f32 v54, v12, s0
	v_or_b32_e32 v12, v58, v91
	v_ashrrev_i32_e32 v13, 31, v12
	v_lshlrev_b64 v[12:13], 1, v[12:13]
	v_lshl_add_u64 v[52:53], s[66:67], 0, v[12:13]
	global_store_short v[52:53], v54, off
	v_lshlrev_b32_e32 v52, 16, v54
	v_or_b32_e32 v92, 0x70, v57
	s_nop 1
	v_add_f32_dpp v213, v52, v52 row_ror:8 row_mask:0xf bank_mask:0xf
	s_nop 1
	v_add_f32_dpp v213, v213, v213 row_ror:4 row_mask:0xf bank_mask:0xf
	v_or_b32_e32 v52, v58, v92
	v_ashrrev_i32_e32 v53, 31, v52
	v_mul_f32_e32 v10, v83, v10
	v_lshlrev_b64 v[52:53], 1, v[52:53]
	v_cvt_pk_bf16_f32 v10, v10, s0
	v_lshl_add_u64 v[54:55], s[66:67], 0, v[52:53]
	global_store_short v[54:55], v10, off
	v_lshlrev_b32_e32 v10, 16, v10
	s_nop 1
	v_add_f32_dpp v214, v10, v10 row_ror:8 row_mask:0xf bank_mask:0xf
	s_nop 1
	v_add_f32_dpp v214, v214, v214 row_ror:4 row_mask:0xf bank_mask:0xf
	v_mul_f32_e32 v10, v83, v11
	v_or_b32_e32 v94, 0x78, v57
	v_cvt_pk_bf16_f32 v93, v10, s0
	v_or_b32_e32 v10, v58, v94
	v_ashrrev_i32_e32 v11, 31, v10
	v_lshlrev_b64 v[10:11], 1, v[10:11]
	v_lshl_add_u64 v[54:55], s[66:67], 0, v[10:11]
	global_store_short v[54:55], v93, off
	v_lshlrev_b32_e32 v54, 16, v93
	s_nop 1
	v_add_f32_dpp v215, v54, v54 row_ror:8 row_mask:0xf bank_mask:0xf
	s_nop 1
	v_add_f32_dpp v215, v215, v215 row_ror:4 row_mask:0xf bank_mask:0xf
	v_lshl_add_u32 v54, v81, 2, v56
	v_lshl_add_u32 v81, v54, 9, v78
	v_or3_b32 v54, v57, v85, v81
	v_ashrrev_i32_e32 v55, 31, v54
	v_mul_f32_e32 v14, v83, v14
	v_lshlrev_b64 v[54:55], 1, v[54:55]
	v_cvt_pk_bf16_f32 v14, v14, s0
	v_lshl_add_u64 v[56:57], s[66:67], 0, v[54:55]
	global_store_short v[56:57], v14, off
	v_lshlrev_b32_e32 v14, 16, v14
	s_nop 1
	v_add_f32_dpp v216, v14, v14 row_ror:8 row_mask:0xf bank_mask:0xf
	s_nop 1
	v_add_f32_dpp v216, v216, v216 row_ror:4 row_mask:0xf bank_mask:0xf
; DI bf16_t f2bf(float f) { return (bf16_t)(pk2(f, 0.f) & 0xffffu); }
; DI float bf2f(bf16_t h) { return __uint_as_float(((unsigned)h) << 16); }
; DI int fragoff(int row, int k, int KS) { return (((row >> 4) * KS + (k >> 5)) << 9) + (((((k >> 3) & 3) << 4) + (row & 15)) << 3) + (k & 7); }
; DI void mlstm_pre(const Params& p, int ch, char* smem) {
;     ...
;     for (int i = 0; i < 32; ++i) {
;       bf16_t kb = f2bf(a[i] * wgt);
;       o_kwT[fragoff(part * 32 + i, t, 2)] = kb;
;       atomicAdd(&s_kw[part * 32 + i], bf2f(kb));
	v_mul_f32_e32 v14, v83, v15
	v_cvt_pk_bf16_f32 v58, v14, s0
	v_or3_b32 v14, v59, v85, v81
	v_ashrrev_i32_e32 v15, 31, v14
	v_lshlrev_b64 v[14:15], 1, v[14:15]
	v_lshl_add_u64 v[56:57], s[66:67], 0, v[14:15]
	global_store_short v[56:57], v58, off
	v_lshlrev_b32_e32 v56, 16, v58
	s_nop 1
	v_add_f32_dpp v217, v56, v56 row_ror:8 row_mask:0xf bank_mask:0xf
	s_nop 1
	v_add_f32_dpp v217, v217, v217 row_ror:4 row_mask:0xf bank_mask:0xf
	v_or3_b32 v56, v60, v85, v81
	v_ashrrev_i32_e32 v57, 31, v56
	v_mul_f32_e32 v34, v83, v34
	v_lshlrev_b64 v[56:57], 1, v[56:57]
	v_cvt_pk_bf16_f32 v34, v34, s0
	v_lshl_add_u64 v[58:59], s[66:67], 0, v[56:57]
	global_store_short v[58:59], v34, off
	v_lshlrev_b32_e32 v34, 16, v34
	s_nop 1
	v_add_f32_dpp v218, v34, v34 row_ror:8 row_mask:0xf bank_mask:0xf
	s_nop 1
	v_add_f32_dpp v218, v218, v218 row_ror:4 row_mask:0xf bank_mask:0xf
	v_mul_f32_e32 v34, v83, v35
	v_cvt_pk_bf16_f32 v60, v34, s0
	v_or3_b32 v34, v61, v85, v81
	v_ashrrev_i32_e32 v35, 31, v34
	v_lshlrev_b64 v[34:35], 1, v[34:35]
	v_lshl_add_u64 v[58:59], s[66:67], 0, v[34:35]
	global_store_short v[58:59], v60, off
	v_lshlrev_b32_e32 v58, 16, v60
	s_nop 1
	v_add_f32_dpp v219, v58, v58 row_ror:8 row_mask:0xf bank_mask:0xf
	s_nop 1
	v_add_f32_dpp v219, v219, v219 row_ror:4 row_mask:0xf bank_mask:0xf
	v_or3_b32 v58, v62, v85, v81
	v_ashrrev_i32_e32 v59, 31, v58
	v_mul_f32_e32 v42, v83, v42
	v_lshlrev_b64 v[58:59], 1, v[58:59]
	v_cvt_pk_bf16_f32 v42, v42, s0
	v_lshl_add_u64 v[60:61], s[66:67], 0, v[58:59]
	global_store_short v[60:61], v42, off
	v_lshlrev_b32_e32 v42, 16, v42
	s_nop 1
	v_add_f32_dpp v220, v42, v42 row_ror:8 row_mask:0xf bank_mask:0xf
	s_nop 1
	v_add_f32_dpp v220, v220, v220 row_ror:4 row_mask:0xf bank_mask:0xf
	v_mul_f32_e32 v42, v83, v43
	v_cvt_pk_bf16_f32 v62, v42, s0
	v_or3_b32 v42, v63, v85, v81
	v_ashrrev_i32_e32 v43, 31, v42
	v_lshlrev_b64 v[42:43], 1, v[42:43]
	v_lshl_add_u64 v[60:61], s[66:67], 0, v[42:43]
	global_store_short v[60:61], v62, off
	v_lshlrev_b32_e32 v60, 16, v62
	s_nop 1
	v_add_f32_dpp v221, v60, v60 row_ror:8 row_mask:0xf bank_mask:0xf
	s_nop 1
	v_add_f32_dpp v221, v221, v221 row_ror:4 row_mask:0xf bank_mask:0xf
	v_or3_b32 v60, v64, v85, v81
	v_ashrrev_i32_e32 v61, 31, v60
	v_mul_f32_e32 v38, v83, v38
	v_lshlrev_b64 v[60:61], 1, v[60:61]
	v_cvt_pk_bf16_f32 v38, v38, s0
	v_lshl_add_u64 v[62:63], s[66:67], 0, v[60:61]
	global_store_short v[62:63], v38, off
	v_lshlrev_b32_e32 v38, 16, v38
	s_nop 1
	v_add_f32_dpp v222, v38, v38 row_ror:8 row_mask:0xf bank_mask:0xf
	s_nop 1
	v_add_f32_dpp v222, v222, v222 row_ror:4 row_mask:0xf bank_mask:0xf
	v_mul_f32_e32 v38, v83, v39
	v_cvt_pk_bf16_f32 v64, v38, s0
	v_or3_b32 v38, v65, v85, v81
	v_ashrrev_i32_e32 v39, 31, v38
	v_lshlrev_b64 v[38:39], 1, v[38:39]
	v_lshl_add_u64 v[62:63], s[66:67], 0, v[38:39]
	global_store_short v[62:63], v64, off
	v_lshlrev_b32_e32 v62, 16, v64
	s_nop 1
	v_add_f32_dpp v223, v62, v62 row_ror:8 row_mask:0xf bank_mask:0xf
	s_nop 1
	v_add_f32_dpp v223, v223, v223 row_ror:4 row_mask:0xf bank_mask:0xf
	v_or3_b32 v62, v86, v85, v81
	v_ashrrev_i32_e32 v63, 31, v62
	v_mul_f32_e32 v4, v83, v4
	v_lshlrev_b64 v[62:63], 1, v[62:63]
	v_cvt_pk_bf16_f32 v4, v4, s0
	v_lshl_add_u64 v[64:65], s[66:67], 0, v[62:63]
	global_store_short v[64:65], v4, off
	v_lshlrev_b32_e32 v4, 16, v4
	s_nop 1
	v_add_f32_dpp v224, v4, v4 row_ror:8 row_mask:0xf bank_mask:0xf
	s_nop 1
	v_add_f32_dpp v224, v224, v224 row_ror:4 row_mask:0xf bank_mask:0xf
	v_mul_f32_e32 v4, v83, v5
	v_cvt_pk_bf16_f32 v86, v4, s0
	v_or3_b32 v4, v87, v85, v81
	v_ashrrev_i32_e32 v5, 31, v4
	v_lshlrev_b64 v[4:5], 1, v[4:5]
	v_lshl_add_u64 v[64:65], s[66:67], 0, v[4:5]
	global_store_short v[64:65], v86, off
	v_lshlrev_b32_e32 v64, 16, v86
	s_nop 1
	v_add_f32_dpp v225, v64, v64 row_ror:8 row_mask:0xf bank_mask:0xf
	s_nop 1
	v_add_f32_dpp v225, v225, v225 row_ror:4 row_mask:0xf bank_mask:0xf
	v_or3_b32 v64, v88, v85, v81
	v_ashrrev_i32_e32 v65, 31, v64
	v_mul_f32_e32 v32, v83, v32
	v_lshlrev_b64 v[64:65], 1, v[64:65]
	v_cvt_pk_bf16_f32 v32, v32, s0
	v_lshl_add_u64 v[86:87], s[66:67], 0, v[64:65]
	global_store_short v[86:87], v32, off
	v_lshlrev_b32_e32 v32, 16, v32
	s_nop 1
	v_add_f32_dpp v226, v32, v32 row_ror:8 row_mask:0xf bank_mask:0xf
	s_nop 1
	v_add_f32_dpp v226, v226, v226 row_ror:4 row_mask:0xf bank_mask:0xf
	v_mul_f32_e32 v32, v83, v33
	v_cvt_pk_bf16_f32 v88, v32, s0
	v_or3_b32 v32, v89, v85, v81
	v_ashrrev_i32_e32 v33, 31, v32
	v_lshlrev_b64 v[32:33], 1, v[32:33]
	v_lshl_add_u64 v[86:87], s[66:67], 0, v[32:33]
	global_store_short v[86:87], v88, off
	v_lshlrev_b32_e32 v86, 16, v88
	s_nop 1
	v_add_f32_dpp v227, v86, v86 row_ror:8 row_mask:0xf bank_mask:0xf
	s_nop 1
	v_add_f32_dpp v227, v227, v227 row_ror:4 row_mask:0xf bank_mask:0xf
	v_or3_b32 v86, v90, v85, v81
	v_ashrrev_i32_e32 v87, 31, v86
	v_mul_f32_e32 v2, v83, v2
	v_lshlrev_b64 v[86:87], 1, v[86:87]
	v_cvt_pk_bf16_f32 v2, v2, s0
	v_lshl_add_u64 v[88:89], s[66:67], 0, v[86:87]
	global_store_short v[88:89], v2, off
	v_lshlrev_b32_e32 v2, 16, v2
	s_nop 1
	v_add_f32_dpp v228, v2, v2 row_ror:8 row_mask:0xf bank_mask:0xf
	s_nop 1
	v_add_f32_dpp v228, v228, v228 row_ror:4 row_mask:0xf bank_mask:0xf
	v_mul_f32_e32 v2, v83, v3
	v_cvt_pk_bf16_f32 v90, v2, s0
	v_or3_b32 v2, v91, v85, v81
	v_ashrrev_i32_e32 v3, 31, v2
	v_lshlrev_b64 v[88:89], 1, v[2:3]
	v_lshl_add_u64 v[2:3], s[66:67], 0, v[88:89]
	global_store_short v[2:3], v90, off
	v_lshlrev_b32_e32 v2, 16, v90
	s_nop 1
	v_add_f32_dpp v229, v2, v2 row_ror:8 row_mask:0xf bank_mask:0xf
	s_nop 1
	v_add_f32_dpp v229, v229, v229 row_ror:4 row_mask:0xf bank_mask:0xf
	v_or3_b32 v2, v92, v85, v81
	v_ashrrev_i32_e32 v3, 31, v2
; DI bf16_t f2bf(float f) { return (bf16_t)(pk2(f, 0.f) & 0xffffu); }
; DI float bf2f(bf16_t h) { return __uint_as_float(((unsigned)h) << 16); }
; DI int fragoff(int row, int k, int KS) { return (((row >> 4) * KS + (k >> 5)) << 9) + (((((k >> 3) & 3) << 4) + (row & 15)) << 3) + (k & 7); }
; DI void mlstm_pre(const Params& p, int ch, char* smem) {
;     ...
;     for (int i = 0; i < 32; ++i) {
;       bf16_t kb = f2bf(a[i] * wgt);
;       o_kwT[fragoff(part * 32 + i, t, 2)] = kb;
;       atomicAdd(&s_kw[part * 32 + i], bf2f(kb));
;     }
;     const uint4* vsrc = (const uint4*)(P + (size_t)(tok0 + t) * 4096 + 3072 + h * 128 + part * 32);
; #pragma unroll
;     for (int q = 0; q < 4; ++q) {
;       uint4 v = vsrc[q];
;       const unsigned uu[4] = {v.x, v.y, v.z, v.w};
; #pragma unroll
;       for (int e = 0; e < 4; ++e) {
;         o_vT[fragoff(part * 32 + 8 * q + 2 * e, t, 2)] = (bf16_t)(uu[e] & 0xffffu);
;         o_vT[fragoff(part * 32 + 8 * q + 2 * e + 1, t, 2)] = (bf16_t)(uu[e] >> 16);
;       }
;     }
	v_mul_f32_e32 v0, v83, v0
	v_lshlrev_b64 v[90:91], 1, v[2:3]
	v_cvt_pk_bf16_f32 v0, v0, s0
	v_lshl_add_u64 v[2:3], s[66:67], 0, v[90:91]
	global_store_short v[2:3], v0, off
	v_lshlrev_b32_e32 v0, 16, v0
	s_nop 1
	v_add_f32_dpp v232, v0, v0 row_ror:8 row_mask:0xf bank_mask:0xf
	s_nop 1
	v_add_f32_dpp v232, v232, v232 row_ror:4 row_mask:0xf bank_mask:0xf
	v_mul_f32_e32 v0, v83, v1
	v_cvt_pk_bf16_f32 v2, v0, s0
	v_or3_b32 v0, v94, v85, v81
	v_ashrrev_i32_e32 v1, 31, v0
	v_lshlrev_b64 v[92:93], 1, v[0:1]
	v_lshl_add_u64 v[0:1], s[66:67], 0, v[92:93]
	global_store_short v[0:1], v2, off
	v_lshlrev_b32_e32 v0, 16, v2
	s_nop 1
	v_add_f32_dpp v233, v0, v0 row_ror:8 row_mask:0xf bank_mask:0xf
	s_nop 1
	v_add_f32_dpp v233, v233, v233 row_ror:4 row_mask:0xf bank_mask:0xf
	s_mov_b64 s[100:101], exec
	s_mov_b32 s98, 0xf000f
	s_mov_b32 s99, 0xf000f
	s_and_b64 exec, s[98:99], s[100:101]
	ds_add_f32 v84, v200 offset:36864
	ds_add_f32 v84, v201 offset:36868
	ds_add_f32 v84, v202 offset:36872
	ds_add_f32 v84, v203 offset:36876
	ds_add_f32 v84, v204 offset:36880
	ds_add_f32 v84, v205 offset:36884
	ds_add_f32 v84, v206 offset:36888
	ds_add_f32 v84, v207 offset:36892
	ds_add_f32 v84, v208 offset:36896
	ds_add_f32 v84, v209 offset:36900
	ds_add_f32 v84, v210 offset:36904
	ds_add_f32 v84, v211 offset:36908
	ds_add_f32 v84, v212 offset:36912
	ds_add_f32 v84, v213 offset:36916
	ds_add_f32 v84, v214 offset:36920
	ds_add_f32 v84, v215 offset:36924
	ds_add_f32 v84, v216 offset:36928
	ds_add_f32 v84, v217 offset:36932
	ds_add_f32 v84, v218 offset:36936
	ds_add_f32 v84, v219 offset:36940
	ds_add_f32 v84, v220 offset:36944
	ds_add_f32 v84, v221 offset:36948
	ds_add_f32 v84, v222 offset:36952
	ds_add_f32 v84, v223 offset:36956
	ds_add_f32 v84, v224 offset:36960
	ds_add_f32 v84, v225 offset:36964
	ds_add_f32 v84, v226 offset:36968
	ds_add_f32 v84, v227 offset:36972
	ds_add_f32 v84, v228 offset:36976
	ds_add_f32 v84, v229 offset:36980
	ds_add_f32 v84, v232 offset:36984
	ds_add_f32 v84, v233 offset:36988
	s_mov_b64 exec, s[100:101]
	v_lshl_add_u64 v[0:1], s[86:87], 0, v[8:9]
	v_lshl_add_u64 v[0:1], v[0:1], 0, s[34:35]
	v_lshl_add_u64 v[8:9], v[0:1], 0, v[28:29]
	s_movk_i32 s8, 0x1000
	v_add_co_u32_e64 v0, s[8:9], s8, v8
	v_lshl_add_u64 v[6:7], s[64:65], 0, v[6:7]
	s_nop 0
	v_addc_co_u32_e64 v1, s[8:9], 0, v9, s[8:9]
	global_load_dwordx4 v[0:3], v[0:1], off offset:2048
	v_lshl_add_u64 v[8:9], v[8:9], 0, s[42:43]
	v_lshl_add_u64 v[4:5], s[64:65], 0, v[4:5]
	s_waitcnt vmcnt(0)
	global_store_short v[6:7], v0, off
	v_lshl_add_u64 v[6:7], s[64:65], 0, v[26:27]
	global_store_short_d16_hi v[6:7], v0, off
	v_lshl_add_u64 v[6:7], s[64:65], 0, v[36:37]
	global_store_short v[6:7], v1, off
	v_lshl_add_u64 v[6:7], s[64:65], 0, v[24:25]
	global_store_short_d16_hi v[6:7], v1, off
	v_lshl_add_u64 v[0:1], s[64:65], 0, v[40:41]
	global_store_short v[0:1], v2, off
	v_lshl_add_u64 v[0:1], s[64:65], 0, v[22:23]
	global_store_short_d16_hi v[0:1], v2, off
	v_lshl_add_u64 v[0:1], s[64:65], 0, v[44:45]
	global_store_short v[0:1], v3, off
	v_lshl_add_u64 v[0:1], s[64:65], 0, v[20:21]
	global_store_short_d16_hi v[0:1], v3, off
	global_load_dwordx4 v[0:3], v[8:9], off offset:16
	v_lshl_add_u64 v[6:7], s[64:65], 0, v[46:47]
	v_and_b32_e32 v21, 31, v30
	s_waitcnt vmcnt(0)
	global_store_short v[6:7], v0, off
	v_lshl_add_u64 v[6:7], s[64:65], 0, v[18:19]
	global_store_short_d16_hi v[6:7], v0, off
	v_lshl_add_u64 v[6:7], s[64:65], 0, v[48:49]
	global_store_short v[6:7], v1, off
	v_lshl_add_u64 v[6:7], s[64:65], 0, v[16:17]
	global_store_short_d16_hi v[6:7], v1, off
	v_lshl_add_u64 v[0:1], s[64:65], 0, v[50:51]
	global_store_short v[0:1], v2, off
	v_lshl_add_u64 v[0:1], s[64:65], 0, v[12:13]
	global_store_short_d16_hi v[0:1], v2, off
	v_lshl_add_u64 v[0:1], s[64:65], 0, v[52:53]
	global_store_short v[0:1], v3, off
	v_lshl_add_u64 v[0:1], s[64:65], 0, v[10:11]
	global_store_short_d16_hi v[0:1], v3, off
	global_load_dwordx4 v[0:3], v[8:9], off offset:32
	v_lshl_add_u64 v[6:7], s[64:65], 0, v[54:55]
	v_bfe_u32 v16, v30, 6, 1
	v_lshl_or_b32 v17, v16, 5, v21
	s_waitcnt vmcnt(0)
	global_store_short v[6:7], v0, off
	v_lshl_add_u64 v[6:7], s[64:65], 0, v[14:15]
	global_store_short_d16_hi v[6:7], v0, off
	v_lshl_add_u64 v[6:7], s[64:65], 0, v[56:57]
	global_store_short v[6:7], v1, off
	v_lshl_add_u64 v[6:7], s[64:65], 0, v[34:35]
	global_store_short_d16_hi v[6:7], v1, off
	v_lshl_add_u64 v[0:1], s[64:65], 0, v[58:59]
	global_store_short v[0:1], v2, off
	v_lshl_add_u64 v[0:1], s[64:65], 0, v[42:43]
	global_store_short_d16_hi v[0:1], v2, off
	v_lshl_add_u64 v[0:1], s[64:65], 0, v[60:61]
	global_store_short v[0:1], v3, off
	v_lshl_add_u64 v[0:1], s[64:65], 0, v[38:39]
	global_store_short_d16_hi v[0:1], v3, off
	global_load_dwordx4 v[0:3], v[8:9], off offset:48
	v_lshl_add_u64 v[6:7], s[64:65], 0, v[62:63]
	s_waitcnt vmcnt(0)
	global_store_short_d16_hi v[4:5], v0, off
	v_lshl_add_u64 v[4:5], s[64:65], 0, v[64:65]
	global_store_short v[4:5], v1, off
	v_lshl_add_u64 v[4:5], s[64:65], 0, v[32:33]
	global_store_short v[6:7], v0, off
	global_store_short_d16_hi v[4:5], v1, off
	v_lshl_add_u64 v[0:1], s[64:65], 0, v[86:87]
	global_store_short v[0:1], v2, off
	v_lshl_add_u64 v[0:1], s[64:65], 0, v[88:89]
	global_store_short_d16_hi v[0:1], v2, off
	v_lshl_add_u64 v[0:1], s[64:65], 0, v[90:91]
	global_store_short v[0:1], v3, off
	v_lshl_add_u64 v[0:1], s[64:65], 0, v[92:93]
	global_store_short_d16_hi v[0:1], v3, off
	v_lshrrev_b32_e32 v1, 1, v30
	v_bfi_b32 v0, s79, v79, v30
	v_and_b32_e32 v4, 16, v1
	v_mad_u64_u32 v[18:19], s[8:9], v0, s75, v[4:5]
	s_waitcnt lgkmcnt(0)
	s_barrier
; #define MFMA32(a, b, c) __builtin_amdgcn_mfma_f32_32x32x16_bf16((a), (b), (c), 0, 0, 0)
; DI int crow32(int r, int half) { return (r & 3) + 8 * (r >> 2) + 4 * half; }
; DI void mlstm_pre(const Params& p, int ch, char* smem) {
;     ...
;   __syncthreads();
;   {
;     const int ti = wave >> 1, tj = wave & 1;
;     f32x16 acc;
; #pragma unroll
;     for (int r = 0; r < 16; ++r) acc[r] = 0.f;
; #pragma unroll
;     for (int s = 0; s < 8; ++s) {
;       const int ko = s * 16 + (lane >> 5) * 8;
;       bf16x8 bk = *(const bf16x8*)(ks + (tj * 32 + (lane & 31)) * 136 + ko);
;       bf16x8 aq = *(const bf16x8*)(qs + (ti * 32 + (lane & 31)) * 136 + ko);
;       acc = MFMA32(aq, bk, acc);
;     }
;     const int j = tj * 32 + (lane & 31);
;     const float cj = s_li[j] - s_bc[j];
; #pragma unroll
;     for (int r = 0; r < 16; ++r) {
;       const int i = ti * 32 + crow32(r, lane >> 5);
;       float pv = (i >= j) ? acc[r] * __expf(s_bc[i] + cj - s_mt[i]) : 0.f;
	ds_read_b128 v[0:3], v18
	v_mad_u32_u24 v19, v17, s75, v4
	ds_read_b128 v[4:7], v19 offset:17408
	ds_read_b128 v[22:25], v19 offset:17440
	ds_read_b128 v[32:35], v18 offset:32
	s_waitcnt lgkmcnt(2)
	v_mfma_f32_32x32x16_bf16 v[0:15], v[0:3], v[4:7], 0
	s_waitcnt lgkmcnt(0)
	v_mfma_f32_32x32x16_bf16 v[0:15], v[32:35], v[22:25], v[0:15]
	ds_read_b128 v[22:25], v18 offset:64
	ds_read_b128 v[32:35], v19 offset:17472
	ds_read_b128 v[36:39], v19 offset:17504
	ds_read_b128 v[40:43], v18 offset:96
	s_waitcnt lgkmcnt(2)
	v_mfma_f32_32x32x16_bf16 v[0:15], v[22:25], v[32:35], v[0:15]
	s_waitcnt lgkmcnt(0)
	v_mfma_f32_32x32x16_bf16 v[0:15], v[40:43], v[36:39], v[0:15]
	ds_read_b128 v[22:25], v18 offset:128
	ds_read_b128 v[32:35], v19 offset:17536
	ds_read_b128 v[36:39], v19 offset:17568
	ds_read_b128 v[40:43], v18 offset:160
	s_waitcnt lgkmcnt(2)
	v_mfma_f32_32x32x16_bf16 v[0:15], v[22:25], v[32:35], v[0:15]
	s_waitcnt lgkmcnt(0)
	v_mfma_f32_32x32x16_bf16 v[0:15], v[40:43], v[36:39], v[0:15]
	ds_read_b128 v[22:25], v18 offset:192
	ds_read_b128 v[32:35], v19 offset:17600
	ds_read_b128 v[36:39], v19 offset:17632
	ds_read_b128 v[40:43], v18 offset:224
	v_mul_i32_i24_e32 v18, 0xfffffef4, v17
	v_mad_u32_u24 v18, v17, s75, v18
	ds_read2st64_b32 v[18:19], v18 offset0:136 offset1:138
	s_waitcnt lgkmcnt(0)
	v_sub_f32_e32 v19, v18, v19
	v_mfma_f32_32x32x16_bf16 v[0:15], v[22:25], v[32:35], v[0:15]
	v_lshrrev_b32_e32 v18, 3, v30
	v_and_b32_e32 v22, 0xffffffe0, v79
	v_and_b32_e32 v23, 4, v18
	v_or_b32_e32 v20, v23, v22
	v_cmp_ge_i32_e64 s[8:9], v20, v17
	v_mov_b32_e32 v24, 0
	v_lshlrev_b32_e32 v18, 2, v20
	v_mfma_f32_32x32x16_bf16 v[0:15], v[40:43], v[36:39], v[0:15]
	s_and_saveexec_b64 s[10:11], s[8:9]
	s_cbranch_execz .LBB0_406
	ds_read2st64_b32 v[24:25], v18 offset0:138 offset1:140
	s_waitcnt lgkmcnt(0)
	v_add_f32_e32 v24, v19, v24
	v_sub_f32_e32 v24, v24, v25
	v_mul_f32_e32 v24, 0x3fb8aa3b, v24
	v_exp_f32_e32 v24, v24
	s_nop 3
	v_mul_f32_e32 v24, v0, v24
